# speedup vs baseline: 1.0055x; 1.0055x over previous
; __device__ __forceinline__ void cvt_range4(const float* __restrict__ src, unsigned char* __restrict__ dst, size_t n32, float sc) {
;     for (size_t i = (size_t)blockIdx.x * 512 + threadIdx.x; i < n32; i += (size_t)gridDim.x * 512) {
;         unsigned w[4];
; #pragma unroll
;         for (int q = 0; q < 4; ++q) {
;             const f32x4 a = *(const f32x4*)(src + i * 32 + q * 8) * sc, b = *(const f32x4*)(src + i * 32 + q * 8 + 4) * sc;
;             unsigned pk = 0u;
;             pk = __builtin_amdgcn_cvt_scalef32_pk_fp4_f32(pk, a[0], a[1], 1.0f, 0);
;             pk = __builtin_amdgcn_cvt_scalef32_pk_fp4_f32(pk, a[2], a[3], 1.0f, 1);
;             pk = __builtin_amdgcn_cvt_scalef32_pk_fp4_f32(pk, b[0], b[1], 1.0f, 2);
;             pk = __builtin_amdgcn_cvt_scalef32_pk_fp4_f32(pk, b[2], b[3], 1.0f, 3);
;             w[q] = pk;
;         }
;         *(uint4*)(dst + i * 16) = make_uint4(w[0], w[1], w[2], w[3]);
;     }
; }
; __device__ void phase_prep(const Params& P, unsigned char* smem) {
;     ...
;         cvt_range4(P.in[I_U], ws + O_UB, (size_t)16384 * 2048 / 32, U_SCALE);
;         cvt_range4(P.in[I_V], ws + O_VB, (size_t)16384 * 2048 / 32, V_SCALE);
.LBB0_26:
	s_lshl_b64 s[6:7], s[2:3], 13
	v_mov_b32_e32 v5, 0
	v_lshl_add_u64 v[6:7], s[6:7], 0, v[4:5]
	s_lshl_b64 s[10:11], s[2:3], 16
	v_and_b32_e32 v4, 0x3c0, v144
	v_lshlrev_b32_e32 v4, 7, v4
	v_and_b32_e32 v60, 63, v144
	v_lshl_add_u32 v4, v60, 5, v4
	v_mov_b32_e32 v62, 0x1000
	v_mov_b32_e32 v63, 0
	v_lshl_add_u64 v[6:7], s[90:91], 0, v[6:7]
	s_mov_b64 s[6:7], 0x1e000000
	v_lshl_add_u64 v[4:5], s[10:11], 0, v[4:5]
	v_lshl_add_u64 v[8:9], v[6:7], 0, s[6:7]
	s_lshl_b64 s[6:7], s[8:9], 13
	v_lshl_add_u64 v[10:11], s[44:45], 0, v[4:5]
	s_lshl_b64 s[8:9], s[8:9], 16
	s_mov_b64 s[10:11], 0
	s_mov_b32 s12, 0x42c00000
	s_mov_b64 s[14:15], 0xfffff
	v_mov_b64_e32 v[12:13], v[2:3]
.LBB0_27:
	s_waitcnt lgkmcnt(0)
	v_lshl_add_u64 v[60:61], v[10:11], 0, v[62:63]
	global_load_dwordx4 v[14:17], v[10:11], off
	global_load_dwordx4 v[18:21], v[10:11], off offset:16
	global_load_dwordx4 v[22:25], v[10:11], off offset:2048
	global_load_dwordx4 v[26:29], v[10:11], off offset:2064
	global_load_dwordx4 v[30:33], v[60:61], off
	global_load_dwordx4 v[34:37], v[60:61], off offset:16
	global_load_dwordx4 v[38:41], v[60:61], off offset:2048
	global_load_dwordx4 v[42:45], v[60:61], off offset:2064
	v_mov_b32_e32 v46, 0
	v_mov_b32_e32 v47, 0
	v_mov_b32_e32 v48, 0
	v_mov_b32_e32 v49, 0
	v_lshl_add_u64 v[12:13], v[12:13], 0, s[0:1]
	v_cmp_lt_u64_e32 vcc, s[14:15], v[12:13]
	v_lshl_add_u64 v[10:11], v[10:11], 0, s[8:9]
	s_or_b64 s[10:11], vcc, s[10:11]
	s_waitcnt vmcnt(7)
	v_pk_mul_f32 v[14:15], v[14:15], s[12:13] op_sel_hi:[1,0]
	v_pk_mul_f32 v[16:17], v[16:17], s[12:13] op_sel_hi:[1,0]
	s_waitcnt vmcnt(5)
	v_pk_mul_f32 v[22:23], v[22:23], s[12:13] op_sel_hi:[1,0]
	v_pk_mul_f32 v[24:25], v[24:25], s[12:13] op_sel_hi:[1,0]
	s_waitcnt vmcnt(3)
	v_pk_mul_f32 v[30:31], v[30:31], s[12:13] op_sel_hi:[1,0]
	v_pk_mul_f32 v[32:33], v[32:33], s[12:13] op_sel_hi:[1,0]
	s_waitcnt vmcnt(1)
	v_pk_mul_f32 v[38:39], v[38:39], s[12:13] op_sel_hi:[1,0]
	v_pk_mul_f32 v[40:41], v[40:41], s[12:13] op_sel_hi:[1,0]
	v_cvt_scalef32_pk_fp4_f32 v46, v14, v15, 1.0
	v_cvt_scalef32_pk_fp4_f32 v47, v22, v23, 1.0
	v_cvt_scalef32_pk_fp4_f32 v48, v30, v31, 1.0
	v_cvt_scalef32_pk_fp4_f32 v49, v38, v39, 1.0
	v_pk_mul_f32 v[18:19], v[18:19], s[12:13] op_sel_hi:[1,0]
	v_pk_mul_f32 v[26:27], v[26:27], s[12:13] op_sel_hi:[1,0]
	v_pk_mul_f32 v[34:35], v[34:35], s[12:13] op_sel_hi:[1,0]
	s_waitcnt vmcnt(0)
	v_pk_mul_f32 v[42:43], v[42:43], s[12:13] op_sel_hi:[1,0]
	v_cvt_scalef32_pk_fp4_f32 v46, v16, v17, 1.0 op_sel:[0,0,1,0]
	v_cvt_scalef32_pk_fp4_f32 v47, v24, v25, 1.0 op_sel:[0,0,1,0]
	v_cvt_scalef32_pk_fp4_f32 v48, v32, v33, 1.0 op_sel:[0,0,1,0]
	v_cvt_scalef32_pk_fp4_f32 v49, v40, v41, 1.0 op_sel:[0,0,1,0]
	v_pk_mul_f32 v[20:21], v[20:21], s[12:13] op_sel_hi:[1,0]
	v_pk_mul_f32 v[28:29], v[28:29], s[12:13] op_sel_hi:[1,0]
	v_pk_mul_f32 v[36:37], v[36:37], s[12:13] op_sel_hi:[1,0]
	v_pk_mul_f32 v[44:45], v[44:45], s[12:13] op_sel_hi:[1,0]
	v_cvt_scalef32_pk_fp4_f32 v46, v18, v19, 1.0 op_sel:[0,0,0,1]
	v_cvt_scalef32_pk_fp4_f32 v47, v26, v27, 1.0 op_sel:[0,0,0,1]
	v_cvt_scalef32_pk_fp4_f32 v48, v34, v35, 1.0 op_sel:[0,0,0,1]
	v_cvt_scalef32_pk_fp4_f32 v49, v42, v43, 1.0 op_sel:[0,0,0,1]
	v_cvt_scalef32_pk_fp4_f32 v46, v20, v21, 1.0 op_sel:[0,0,1,1]
	v_cvt_scalef32_pk_fp4_f32 v47, v28, v29, 1.0 op_sel:[0,0,1,1]
	v_cvt_scalef32_pk_fp4_f32 v48, v36, v37, 1.0 op_sel:[0,0,1,1]
	v_cvt_scalef32_pk_fp4_f32 v49, v44, v45, 1.0 op_sel:[0,0,1,1]
	global_store_dwordx4 v[8:9], v[46:49], off
	v_lshl_add_u64 v[8:9], v[8:9], 0, s[6:7]
	s_andn2_b64 exec, exec, s[10:11]
	s_cbranch_execnz .LBB0_27
	s_or_b64 exec, exec, s[10:11]
	s_mov_b64 s[10:11], 0x22000000
	v_lshl_add_u64 v[6:7], v[6:7], 0, s[10:11]
	v_lshl_add_u64 v[4:5], s[46:47], 0, v[4:5]
	s_mov_b64 s[10:11], 0
	s_mov_b32 s12, 0x41c00000
	s_mov_b64 s[14:15], 0xfffff
.LBB0_29:
	v_lshl_add_u64 v[60:61], v[4:5], 0, v[62:63]
	global_load_dwordx4 v[8:11], v[4:5], off
	global_load_dwordx4 v[12:15], v[4:5], off offset:16
	global_load_dwordx4 v[16:19], v[4:5], off offset:2048
	global_load_dwordx4 v[20:23], v[4:5], off offset:2064
	global_load_dwordx4 v[24:27], v[60:61], off
	global_load_dwordx4 v[28:31], v[60:61], off offset:16
	global_load_dwordx4 v[32:35], v[60:61], off offset:2048
	global_load_dwordx4 v[36:39], v[60:61], off offset:2064
	v_mov_b32_e32 v40, 0
	v_mov_b32_e32 v41, 0
	v_mov_b32_e32 v42, 0
	v_mov_b32_e32 v43, 0
	v_lshl_add_u64 v[2:3], v[2:3], 0, s[0:1]
	v_cmp_lt_u64_e32 vcc, s[14:15], v[2:3]
	v_lshl_add_u64 v[4:5], v[4:5], 0, s[8:9]
	s_or_b64 s[10:11], vcc, s[10:11]
	s_waitcnt vmcnt(7)
	v_pk_mul_f32 v[8:9], v[8:9], s[12:13] op_sel_hi:[1,0]
	v_pk_mul_f32 v[10:11], v[10:11], s[12:13] op_sel_hi:[1,0]
	s_waitcnt vmcnt(5)
	v_pk_mul_f32 v[16:17], v[16:17], s[12:13] op_sel_hi:[1,0]
	v_pk_mul_f32 v[18:19], v[18:19], s[12:13] op_sel_hi:[1,0]
	s_waitcnt vmcnt(3)
	v_pk_mul_f32 v[24:25], v[24:25], s[12:13] op_sel_hi:[1,0]
	v_pk_mul_f32 v[26:27], v[26:27], s[12:13] op_sel_hi:[1,0]
	s_waitcnt vmcnt(1)
	v_pk_mul_f32 v[32:33], v[32:33], s[12:13] op_sel_hi:[1,0]
	v_pk_mul_f32 v[34:35], v[34:35], s[12:13] op_sel_hi:[1,0]
	v_cvt_scalef32_pk_fp4_f32 v40, v8, v9, 1.0
	v_cvt_scalef32_pk_fp4_f32 v41, v16, v17, 1.0
	v_cvt_scalef32_pk_fp4_f32 v42, v24, v25, 1.0
	v_cvt_scalef32_pk_fp4_f32 v43, v32, v33, 1.0
	v_pk_mul_f32 v[12:13], v[12:13], s[12:13] op_sel_hi:[1,0]
	v_pk_mul_f32 v[20:21], v[20:21], s[12:13] op_sel_hi:[1,0]
	v_pk_mul_f32 v[28:29], v[28:29], s[12:13] op_sel_hi:[1,0]
	s_waitcnt vmcnt(0)
	v_pk_mul_f32 v[36:37], v[36:37], s[12:13] op_sel_hi:[1,0]
	v_cvt_scalef32_pk_fp4_f32 v40, v10, v11, 1.0 op_sel:[0,0,1,0]
	v_cvt_scalef32_pk_fp4_f32 v41, v18, v19, 1.0 op_sel:[0,0,1,0]
	v_cvt_scalef32_pk_fp4_f32 v42, v26, v27, 1.0 op_sel:[0,0,1,0]
	v_cvt_scalef32_pk_fp4_f32 v43, v34, v35, 1.0 op_sel:[0,0,1,0]
	v_pk_mul_f32 v[14:15], v[14:15], s[12:13] op_sel_hi:[1,0]
	v_pk_mul_f32 v[22:23], v[22:23], s[12:13] op_sel_hi:[1,0]
	v_pk_mul_f32 v[30:31], v[30:31], s[12:13] op_sel_hi:[1,0]
	v_pk_mul_f32 v[38:39], v[38:39], s[12:13] op_sel_hi:[1,0]
	v_cvt_scalef32_pk_fp4_f32 v40, v12, v13, 1.0 op_sel:[0,0,0,1]
	v_cvt_scalef32_pk_fp4_f32 v41, v20, v21, 1.0 op_sel:[0,0,0,1]
	v_cvt_scalef32_pk_fp4_f32 v42, v28, v29, 1.0 op_sel:[0,0,0,1]
	v_cvt_scalef32_pk_fp4_f32 v43, v36, v37, 1.0 op_sel:[0,0,0,1]
	v_cvt_scalef32_pk_fp4_f32 v40, v14, v15, 1.0 op_sel:[0,0,1,1]
	v_cvt_scalef32_pk_fp4_f32 v41, v22, v23, 1.0 op_sel:[0,0,1,1]
	v_cvt_scalef32_pk_fp4_f32 v42, v30, v31, 1.0 op_sel:[0,0,1,1]
	v_cvt_scalef32_pk_fp4_f32 v43, v38, v39, 1.0 op_sel:[0,0,1,1]
	global_store_dwordx4 v[6:7], v[40:43], off
	v_lshl_add_u64 v[6:7], v[6:7], 0, s[6:7]
	s_andn2_b64 exec, exec, s[10:11]
	s_cbranch_execnz .LBB0_29
	s_or_b64 exec, exec, s[10:11]
	s_or_b64 exec, exec, s[4:5]
	s_cmpk_gt_i32 s2, 0x22ff
	s_cbranch_scc1 .LBB0_86

; #define PEER_BAR() asm volatile("" ::: "memory")
; __device__ void phase_peer(const Params& P, unsigned char* smem) {
;     const int tid = threadIdx.x, lane = tid & 63, wid = tid >> 6, l15 = lane & 15, l4 = lane >> 4;
;     float* sv = (float*)(smem + 98304);
;     unsigned char* si = smem + 131072;
;     const bf16_t* QP = (const bf16_t*)(P.ws + O_R3);
;     const bf16_t* SKB = (const bf16_t*)(P.ws + O_SKB);
;     const unsigned char* UB8 = P.ws + O_UB;
;     const unsigned char* VB8 = P.ws + O_VB;
;     bf16_t* H2B = (bf16_t*)(P.ws + O_R1);
;     float* rinv3 = (float*)(P.ws + O_SMALL) + 2 * T;
;     const float* gffn = P.in[I_NFFN];
;     float* WL = (float*)(P.ws + O_UB + 16 * MiB);
;     unsigned short* IDS = (unsigned short*)(P.ws + O_UB + 32 * MiB);
;     ...
;             const int tok = wid + 8 * ti; const size_t gtok = (size_t)tok0 + tok;
;             const bf16_t* hrow = H2B + gtok * D + lane * 32;
;             f32x2 xn2[16]; float ss = 0.f;
; #pragma unroll
;             for (int q = 0; q < 8; ++q) {
;                 const f32x4 v = unpk4(*(const uint2*)(hrow + q * 4)); const f32x4 gv = *(const f32x4*)(gffn + lane * 32 + q * 4);
;                 ss += v[0] * v[0] + v[1] * v[1] + v[2] * v[2] + v[3] * v[3];
;                 xn2[q * 2] = (f32x2){v[0] * gv[0], v[1] * gv[1]}; xn2[q * 2 + 1] = (f32x2){v[2] * gv[2], v[3] * gv[3]};
;             }
;             ss = wave_sum(ss);
;             const float ri = rsqrtf(ss * (1.f / D) + EPS);
;             const int e_lane = ((lane >> 2) & 1) + 2 * ((lane >> 3) & 1) + 4 * ((lane >> 4) & 1) + 8 * (lane >> 5);
;     ...
; #pragma unroll 1
;             for (int hh = 0; hh < 8; ++hh) {
;                 const unsigned short* idp = ids + tok * 128 + hh * 16;
;                 float p[16];
;                 uint4 ubA[8], ubB[8];
;                 PEER_LOADT(ubA, UB8, idp, 0); PEER_BAR();
;                 PEER_LOADT(ubB, UB8, idp, 1); PEER_BAR(); PEER_U4(ubA, 0); PEER_BAR();
;                 PEER_U4(ubB, 1); PEER_BAR();
;                 float r8[8], r4[4], r2[2], r1;
;                 { const bool b = lane & 32;
; #pragma unroll
;                   for (int i = 0; i < 8; ++i) { const float mine = b ? p[i + 8] : p[i], send = b ? p[i] : p[i + 8]; r8[i] = mine + __shfl_xor(send, 32); } }
;                 { const bool b = lane & 16;
; #pragma unroll
.LBB0_951:
	s_add_u32 s26, s90, 0x5840000
	s_addc_u32 s27, s91, 0
	s_cmp_lt_i32 s92, 9
	s_cselect_b64 s[0:1], -1, 0
	s_cmp_gt_i32 s93, 8
	s_cselect_b64 s[4:5], -1, 0
	s_and_b64 s[0:1], s[0:1], s[4:5]
	s_andn2_b64 vcc, exec, s[0:1]
	s_cbranch_vccnz .LBB0_1043
	s_cmpk_gt_i32 s2, 0x3ff
	s_cbranch_scc1 .LBB0_989
	v_readlane_b32 s0, v248, 1
	v_readlane_b32 s1, v248, 2
	s_load_dword s0, s[0:1], 0x10
	v_and_b32_e32 v48, 48, v144
	v_mov_b32_e32 v49, 0
	v_lshl_add_u64 v[0:1], s[90:91], 0, v[48:49]
	v_and_b32_e32 v107, 63, v144
	s_waitcnt lgkmcnt(0)
	s_lshr_b32 s0, s0, 16
	s_cmp_lg_u32 s0, 0
	s_cselect_b64 s[0:1], -1, 0
	s_cmp_lg_u64 s[0:1], 0
	s_mov_b64 s[0:1], 0x4500000
	v_bfe_u32 v2, v144, 4, 2
	v_lshl_add_u64 v[52:53], v[0:1], 0, s[0:1]
	v_readlane_b32 s8, v248, 22
	v_lshrrev_b32_e32 v0, 2, v144
	v_lshl_add_u64 v[50:51], s[40:41], 0, v[48:49]
	v_lshlrev_b32_e32 v109, 2, v2
	v_lshlrev_b32_e32 v48, 4, v107
	v_readlane_b32 s9, v248, 23
	v_and_b32_e32 v2, 11, v0
	v_and_b32_e32 v0, 32, v144
	v_lshl_add_u64 v[64:65], s[34:35], 0, v[48:49]
	v_lshlrev_b32_e32 v48, 5, v107
	v_readlane_b32 s10, v248, 24
	v_readlane_b32 s11, v248, 25
	v_cmp_eq_u32_e64 s[8:9], 0, v0
	v_and_b32_e32 v0, 16, v144
	v_readlane_b32 s12, v248, 26
	v_readlane_b32 s13, v248, 27
	v_lshl_add_u64 v[54:55], s[10:11], 0, v[48:49]
	v_cmp_eq_u32_e64 s[10:11], 0, v0
	v_and_b32_e32 v0, 8, v144
	v_readlane_b32 s14, v248, 28
	v_readlane_b32 s15, v248, 29
	v_cmp_eq_u32_e64 s[12:13], 0, v0
	v_and_b32_e32 v0, 4, v144
	v_readlane_b32 s16, v248, 30
	v_readlane_b32 s17, v248, 31
	v_cmp_eq_u32_e64 s[14:15], 0, v0
	v_and_b32_e32 v0, 3, v144
	v_and_b32_e32 v106, 15, v144
	s_movk_i32 s0, 0x100
	v_cmp_eq_u32_e64 s[16:17], 0, v0
	v_lshlrev_b32_e32 v0, 5, v146
	v_bfe_u32 v4, v107, 4, 1
	s_addc_u32 s3, s94, 0
	v_cmp_gt_u32_e64 s[6:7], s0, v144
	s_add_i32 s0, 0, 0x18000
	v_lshl_add_u32 v149, v106, 8, v0
	v_lshlrev_b32_e32 v0, 9, v146
	v_lshlrev_b32_e32 v1, 4, v4
	v_lshlrev_b32_e32 v5, 2, v2
	v_lshlrev_b32_e32 v110, 5, v144
	v_lshl_add_u32 v111, v144, 7, s0
	s_add_i32 s0, 0, 0x20000
	v_lshlrev_b32_e32 v48, 4, v107
	v_or3_b32 v0, v0, v1, v5
	v_and_or_b32 v5, v109, 4, v2
	v_add_u32_e32 v113, s0, v110
	v_lshl_add_u64 v[56:57], s[90:91], 0, v[48:49]
	s_mov_b64 s[0:1], 0x1e000000
	v_add_u32_e32 v0, 0, v0
	v_lshlrev_b32_e32 v48, 2, v5
	v_lshl_add_u64 v[58:59], v[56:57], 0, s[0:1]
	v_add_u32_e32 v151, 0x2000, v0
	v_lshl_add_u64 v[0:1], s[90:91], 0, v[48:49]
	s_mov_b64 s[0:1], 0x1f000000
	v_lshlrev_b32_e32 v48, 1, v5
	v_lshl_add_u64 v[60:61], v[0:1], 0, s[0:1]
	v_lshl_add_u64 v[0:1], s[90:91], 0, v[48:49]
	s_mov_b64 s[0:1], 0x20000000
	v_lshl_add_u64 v[62:63], v[0:1], 0, s[0:1]
	v_lshlrev_b32_e32 v0, 8, v146
	v_lshlrev_b32_e32 v1, 3, v4
	v_lshlrev_b32_e32 v2, 1, v2
	v_or3_b32 v1, v0, v1, v2
	v_add_u32_e32 v153, 0, v0
	v_lshlrev_b32_e32 v3, 7, v106
	s_lshl_b32 s28, s2, 5
	v_mbcnt_lo_u32_b32 v0, -1, 0
	s_mov_b32 s43, 0
	v_lshlrev_b32_e32 v108, 1, v146
	v_cmp_gt_u32_e64 s[4:5], 16, v107
	v_lshlrev_b32_e32 v114, 6, v144
	v_or_b32_e32 v115, 1, v109
	v_or_b32_e32 v116, 2, v109
	v_or_b32_e32 v117, 3, v109
	v_or_b32_e32 v118, 16, v109
	v_or_b32_e32 v119, 17, v109
	v_or_b32_e32 v120, 18, v109
	v_or_b32_e32 v121, 19, v109
	v_or_b32_e32 v122, 32, v109
	v_or_b32_e32 v123, 33, v109
	v_or_b32_e32 v124, 34, v109
	v_or_b32_e32 v125, 35, v109
	v_or_b32_e32 v126, 48, v109
	v_or_b32_e32 v127, 49, v109
	v_or_b32_e32 v128, 50, v109
	v_or_b32_e32 v129, 51, v109
	v_or_b32_e32 v130, 64, v109
	v_or_b32_e32 v131, 0x41, v109
	v_or_b32_e32 v132, 0x42, v109
	v_or_b32_e32 v133, 0x43, v109
	v_or_b32_e32 v134, 0x50, v109
	v_or_b32_e32 v135, 0x51, v109
	v_or_b32_e32 v136, 0x52, v109
	v_or_b32_e32 v137, 0x53, v109
	v_or_b32_e32 v138, 0x60, v109
	v_or_b32_e32 v139, 0x61, v109
	v_or_b32_e32 v140, 0x62, v109
	v_or_b32_e32 v141, 0x63, v109
	v_or_b32_e32 v142, 0x70, v109
	v_or_b32_e32 v143, 0x71, v109
	v_or_b32_e32 v145, 0x72, v109
	v_or_b32_e32 v148, 0x73, v109
	s_movk_i32 s29, 0x1000
	v_add_u32_e32 v150, 0x1000, v149
	s_lshl_b32 s48, s3, 2
	s_movk_i32 s49, 0x2000
	v_mov_b32_e32 v147, v49
	s_lshl_b32 s50, s3, 7
	s_lshl_b32 s51, s3, 5
	v_add_u32_e32 v152, 0, v1
	v_lshlrev_b32_e32 v154, 1, v3
	s_movk_i32 s52, 0x3000
	s_movk_i32 s53, 0x4000
	s_movk_i32 s54, 0x5000
	s_movk_i32 s55, 0x6000
	s_movk_i32 s56, 0x7000
	s_brev_b32 s57, 1
	s_movk_i32 s58, 0xff80
	s_movk_i32 s59, 0x7f
	s_movk_i32 s60, 0xff00
	s_mov_b32 s61, 0xf149f2ca
	v_mov_b32_e32 v155, 0x358637bd
	s_mov_b32 s62, 0x800000
	s_mov_b32 s63, 0x42c00000
	s_mov_b32 s64, 0x378e98ab
	s_mov_b32 s65, 0x3b7cd369
	s_mov_b32 s66, 0xbcc618b2
	s_mov_b32 s67, 0x3dda74e4
	s_mov_b32 s68, 0x3f228afd
	s_mov_b32 s69, 0x3e03c728
	s_mov_b32 s70, 0xbfb8aa3b
	s_mov_b32 s71, 0x42ce8ed0
	s_mov_b32 s72, 0xc2b17218
	v_mov_b32_e32 v156, 0x3ba10414
	s_brev_b32 s73, -2
	s_mov_b64 s[38:39], 0x1000
	s_mov_b64 s[44:45], 0x800
	v_mbcnt_hi_u32_b32 v112, -1, v0
	v_bfrev_b32_e32 v157, 1
	v_mov_b32_e32 v158, 0xb9c68948
	v_mov_b32_e32 v159, 0x7f800000
	s_mov_b32 s74, s28
	s_mov_b32 s75, s2
	v_readlane_b32 s18, v248, 32
	v_readlane_b32 s19, v248, 33
	v_readlane_b32 s20, v248, 34
	v_readlane_b32 s21, v248, 35
	v_readlane_b32 s22, v248, 36
	v_readlane_b32 s23, v248, 37
	s_branch .LBB0_955

; __device__ __forceinline__ f32x4 unpk4(uint2 u) { f32x4 r; r[0] = __uint_as_float(u.x << 16); r[1] = __uint_as_float(u.x & 0xffff0000u); r[2] = __uint_as_float(u.y << 16); r[3] = __uint_as_float(u.y & 0xffff0000u); return r; }
; __device__ __forceinline__ float gelu_exact(float x) { return 0.5f * x * (1.f + erff(x * 0.70710678118654752f)); }
; __device__ void phase_peer(const Params& P, unsigned char* smem) {
;     ...
;             const int tok = wid + 8 * ti; const size_t gtok = (size_t)tok0 + tok;
;             const bf16_t* hrow = H2B + gtok * D + lane * 32;
;             f32x2 xn2[16]; float ss = 0.f;
; #pragma unroll
;             for (int q = 0; q < 8; ++q) {
;                 const f32x4 v = unpk4(*(const uint2*)(hrow + q * 4)); const f32x4 gv = *(const f32x4*)(gffn + lane * 32 + q * 4);
;                 ss += v[0] * v[0] + v[1] * v[1] + v[2] * v[2] + v[3] * v[3];
;                 xn2[q * 2] = (f32x2){v[0] * gv[0], v[1] * gv[1]}; xn2[q * 2 + 1] = (f32x2){v[2] * gv[2], v[3] * gv[3]};
;             }
;             ss = wave_sum(ss);
;             const float ri = rsqrtf(ss * (1.f / D) + EPS);
;     ...
;                 const float wl = (ev / esum) * gelu_exact(r1 * (ri / U_SCALE)) * (1.f / V_SCALE);
.LBB0_973:
	v_lshl_add_u32 v48, s1, 3, v146
	v_lshl_add_u64 v[0:1], v[48:49], 0, s[18:19]
	v_lshlrev_b64 v[0:1], 12, v[0:1]
	v_lshl_add_u64 v[12:13], v[64:65], 0, v[0:1]
	s_waitcnt lgkmcnt(0)
	global_load_dwordx4 v[0:3], v[12:13], off
	global_load_dwordx4 v[4:7], v[12:13], off offset:1024
	global_load_dwordx4 v[8:11], v[12:13], off offset:2048
	s_nop 0
	global_load_dwordx4 v[12:15], v[12:13], off offset:3072
	s_nop 0
	v_mov_b32_e32 v194, 0x1000
	v_mov_b32_e32 v195, 0
	v_lshl_add_u64 v[196:197], v[54:55], 0, v[194:195]
	global_load_dwordx4 v[16:19], v[196:197], off offset:16
	global_load_dwordx4 v[20:23], v[196:197], off offset:2064
	global_load_dwordx4 v[24:27], v[54:55], off offset:2064
	global_load_dwordx4 v[28:31], v[54:55], off offset:2048
	global_load_dwordx4 v[32:35], v[54:55], off offset:16
	global_load_dwordx4 v[36:39], v[54:55], off
	global_load_dwordx4 v[40:43], v[196:197], off offset:2048
	global_load_dwordx4 v[44:47], v[196:197], off
	s_mov_b32 s23, 0
	s_waitcnt vmcnt(11)
	v_lshlrev_b32_e32 v78, 16, v0
	v_and_b32_e32 v79, 0xffff0000, v0
	v_lshlrev_b32_e32 v82, 16, v2
	v_and_b32_e32 v83, 0xffff0000, v2
	s_waitcnt vmcnt(9)
	v_and_b32_e32 v95, 0xffff0000, v8
	v_lshlrev_b32_e32 v74, 16, v10
	v_and_b32_e32 v75, 0xffff0000, v10
	v_lshlrev_b32_e32 v0, 16, v1
	v_and_b32_e32 v1, 0xffff0000, v1
	v_lshlrev_b32_e32 v2, 16, v3
	v_and_b32_e32 v3, 0xffff0000, v3
	v_lshlrev_b32_e32 v94, 16, v8
	v_pk_mul_f32 v[80:81], v[78:79], v[78:79]
	v_pk_mul_f32 v[88:89], v[82:83], v[82:83]
	s_waitcnt vmcnt(7)
	v_pk_mul_f32 v[70:71], v[16:17], v[74:75]
	v_mov_b32_e32 v17, v74
	v_mov_b32_e32 v74, v95
	v_lshlrev_b32_e32 v86, 16, v4
	v_and_b32_e32 v87, 0xffff0000, v4
	v_pk_mul_f32 v[84:85], v[0:1], v[0:1]
	v_pk_mul_f32 v[92:93], v[2:3], v[2:3]
	v_mov_b32_e32 v16, v94
	v_pk_mul_f32 v[74:75], v[74:75], v[74:75]
	v_add_f32_e32 v48, v88, v89
	v_add_f32_e32 v80, v80, v81
	v_lshlrev_b32_e32 v4, 16, v5
	v_and_b32_e32 v5, 0xffff0000, v5
	v_lshlrev_b32_e32 v90, 16, v6
	v_and_b32_e32 v91, 0xffff0000, v6
	v_pk_mul_f32 v[96:97], v[86:87], v[86:87]
	v_pk_fma_f32 v[16:17], v[16:17], v[16:17], v[74:75]
	v_add_f32_e32 v48, v48, v92
	v_add_f32_e32 v74, v80, v84
	v_lshlrev_b32_e32 v6, 16, v7
	v_and_b32_e32 v7, 0xffff0000, v7
	v_pk_mul_f32 v[98:99], v[4:5], v[4:5]
	v_pk_mul_f32 v[102:103], v[90:91], v[90:91]
	v_add_f32_e32 v81, v96, v97
	v_add_f32_e32 v48, v93, v48
	v_add_f32_e32 v74, v85, v74
	v_lshlrev_b32_e32 v8, 16, v9
	v_lshlrev_b32_e32 v10, 16, v11
	v_and_b32_e32 v101, 0xffff0000, v12
	v_lshlrev_b32_e32 v76, 16, v14
	v_and_b32_e32 v77, 0xffff0000, v14
	v_pk_mul_f32 v[104:105], v[6:7], v[6:7]
	v_add_f32_e32 v75, v81, v98
	v_add_f32_e32 v48, v74, v48
	v_add_f32_e32 v74, v102, v103
	v_and_b32_e32 v9, 0xffff0000, v9
	v_and_b32_e32 v11, 0xffff0000, v11
	v_lshlrev_b32_e32 v100, 16, v12
	v_mov_b32_e32 v172, v8
	v_mov_b32_e32 v173, v10
	s_waitcnt vmcnt(6)
	v_pk_mul_f32 v[72:73], v[20:21], v[76:77]
	v_mov_b32_e32 v21, v76
	v_mov_b32_e32 v76, v101
	v_add_f32_e32 v75, v99, v75
	v_add_f32_e32 v74, v74, v104
	v_lshlrev_b32_e32 v12, 16, v13
	v_lshlrev_b32_e32 v14, 16, v15
	v_mov_b32_e32 v174, v9
	v_mov_b32_e32 v175, v11
	v_mov_b32_e32 v20, v100
	v_pk_mul_f32 v[76:77], v[76:77], v[76:77]
	v_pk_fma_f32 v[16:17], v[172:173], v[172:173], v[16:17]
	v_add_f32_e32 v48, v48, v75
	v_add_f32_e32 v74, v105, v74
	v_and_b32_e32 v13, 0xffff0000, v13
	v_and_b32_e32 v15, 0xffff0000, v15
	v_mov_b32_e32 v176, v12
	v_mov_b32_e32 v177, v14
	v_pk_fma_f32 v[20:21], v[20:21], v[20:21], v[76:77]
	v_pk_fma_f32 v[16:17], v[174:175], v[174:175], v[16:17]
	v_add_f32_e32 v48, v48, v74
	v_mov_b32_e32 v178, v13
	v_mov_b32_e32 v179, v15
	v_pk_fma_f32 v[20:21], v[176:177], v[176:177], v[20:21]
	v_add_f32_e32 v16, v48, v16
	v_pk_fma_f32 v[20:21], v[178:179], v[178:179], v[20:21]
	v_add_f32_e32 v16, v16, v17
	v_add_f32_e32 v16, v16, v20
	v_add_f32_e32 v16, v16, v21
	ds_bpermute_b32 v17, v163, v16
	s_waitcnt vmcnt(2)
	v_pk_mul_f32 v[80:81], v[38:39], v[0:1]
	v_pk_mul_f32 v[84:85], v[34:35], v[2:3]
	v_pk_mul_f32 v[88:89], v[30:31], v[4:5]
	v_mov_b64_e32 v[74:75], v[68:69]
	s_waitcnt lgkmcnt(0)
	v_add_f32_e32 v16, v16, v17
	ds_bpermute_b32 v17, v164, v16
	v_mov_b64_e32 v[76:77], v[66:67]
	v_mov_b32_e32 v48, v171
	v_pk_mul_f32 v[78:79], v[36:37], v[78:79]
	v_pk_mul_f32 v[82:83], v[32:33], v[82:83]
	s_waitcnt lgkmcnt(0)
	v_add_f32_e32 v16, v16, v17
	ds_bpermute_b32 v17, v165, v16
	v_pk_mul_f32 v[86:87], v[28:29], v[86:87]
	v_pk_mul_f32 v[90:91], v[24:25], v[90:91]
	v_pk_mul_f32 v[92:93], v[26:27], v[6:7]
	s_waitcnt vmcnt(0)
	v_pk_mul_f32 v[94:95], v[44:45], v[94:95]
	s_waitcnt lgkmcnt(0)
	v_add_f32_e32 v16, v16, v17
	ds_bpermute_b32 v17, v166, v16
	v_pk_mul_f32 v[96:97], v[46:47], v[8:9]
	v_pk_mul_f32 v[98:99], v[18:19], v[10:11]
	v_pk_mul_f32 v[100:101], v[40:41], v[100:101]
	v_pk_mul_f32 v[102:103], v[42:43], v[12:13]
	s_waitcnt lgkmcnt(0)
	v_add_f32_e32 v0, v16, v17
	ds_bpermute_b32 v1, v167, v0
	v_pk_mul_f32 v[104:105], v[22:23], v[14:15]
	s_waitcnt lgkmcnt(0)
	v_add_f32_e32 v0, v0, v1
	ds_bpermute_b32 v1, v168, v0
	s_waitcnt lgkmcnt(0)
	v_add_f32_e32 v0, v0, v1
	v_fmamk_f32 v0, v0, 0x3a000000, v155
	v_mul_f32_e32 v1, 0x4b800000, v0
	v_cmp_gt_f32_e32 vcc, s62, v0
	s_nop 1
	v_cndmask_b32_e32 v0, v0, v1, vcc
	v_rsq_f32_e32 v0, v0
	s_nop 0
	v_mul_f32_e32 v1, 0x45800000, v0
	v_cndmask_b32_e32 v172, v0, v1, vcc
	v_div_scale_f32 v0, s[20:21], s63, s63, v172
	v_rcp_f32_e32 v1, v0
	v_div_scale_f32 v2, vcc, v172, s63, v172
	v_fma_f32 v3, -v0, v1, 1.0
	v_fmac_f32_e32 v1, v3, v1
	v_mul_f32_e32 v3, v2, v1
	v_fma_f32 v4, -v0, v3, v2
	v_fmac_f32_e32 v3, v4, v1
	v_fma_f32 v0, -v0, v3, v2
	v_div_fmas_f32 v0, v0, v1, v3
	v_div_fixup_f32 v173, v0, s63, v172
	s_branch .LBB0_975

; #define PEER_BAR() asm volatile("" ::: "memory")
; #define PEER_LOADV(buf, b) do { _Pragma("unroll") for (int e = 0; e < 8; ++e) { const unsigned id = (unsigned)__builtin_amdgcn_readlane((int)idv, (b) * 8 + e); \
;         buf[e] = *(const uint4*)(VB8 + (size_t)id * 1024 + lane * 16); } } while (0)
; __device__ void phase_peer(const Params& P, unsigned char* smem) {
;     ...
; #pragma unroll 1
;             for (int hh = 0; hh < 8; ++hh) {
;                 const unsigned idv = (unsigned)IDS[gtok * 128 + hh * 16 + (lane & 15)];
;                 const float wv = WL[gtok * 128 + hh * 16 + (lane & 15)];
;                 uint4 vbA[8], vbB[8];
;                 PEER_LOADV(vbA, 0); PEER_BAR();
;                 PEER_LOADV(vbB, 1); PEER_BAR(); PEER_V4(vbA, 0); PEER_BAR();
;                 PEER_V4(vbB, 1);
.LBB0_986:
	v_lshl_add_u64 v[0:1], v[74:75], 0, s[0:1]
	global_load_ushort v2, v[0:1], off
	global_load_dword v68, v[78:79], off
	v_lshl_add_u64 v[78:79], v[78:79], 0, 64
	s_waitcnt vmcnt(1)
	v_readlane_b32 s4, v2, 0
	s_lshl_b64 s[12:13], s[4:5], 10
	v_lshl_add_u64 v[0:1], v[66:67], 0, s[12:13]
	global_load_dwordx4 v[60:63], v[0:1], off
	v_readlane_b32 s4, v2, 1
	s_lshl_b64 s[12:13], s[4:5], 10
	v_lshl_add_u64 v[0:1], v[66:67], 0, s[12:13]
	global_load_dwordx4 v[56:59], v[0:1], off
	v_readlane_b32 s4, v2, 2
	s_lshl_b64 s[12:13], s[4:5], 10
	v_lshl_add_u64 v[0:1], v[66:67], 0, s[12:13]
	global_load_dwordx4 v[52:55], v[0:1], off
	v_readlane_b32 s4, v2, 3
	s_lshl_b64 s[12:13], s[4:5], 10
	v_lshl_add_u64 v[0:1], v[66:67], 0, s[12:13]
	global_load_dwordx4 v[48:51], v[0:1], off
	v_readlane_b32 s4, v2, 4
	s_lshl_b64 s[12:13], s[4:5], 10
	v_lshl_add_u64 v[0:1], v[66:67], 0, s[12:13]
	global_load_dwordx4 v[44:47], v[0:1], off
	v_readlane_b32 s4, v2, 5
	s_lshl_b64 s[12:13], s[4:5], 10
	v_lshl_add_u64 v[0:1], v[66:67], 0, s[12:13]
	global_load_dwordx4 v[40:43], v[0:1], off
	v_readlane_b32 s4, v2, 6
	s_lshl_b64 s[12:13], s[4:5], 10
	v_readlane_b32 s4, v2, 7
	v_lshl_add_u64 v[0:1], v[66:67], 0, s[12:13]
	s_lshl_b64 s[12:13], s[4:5], 10
	v_readlane_b32 s4, v2, 8
	global_load_dwordx4 v[36:39], v[0:1], off
	v_lshl_add_u64 v[0:1], v[66:67], 0, s[12:13]
	s_lshl_b64 s[12:13], s[4:5], 10
	v_readlane_b32 s4, v2, 9
	global_load_dwordx4 v[32:35], v[0:1], off
	v_lshl_add_u64 v[0:1], v[66:67], 0, s[12:13]
	s_lshl_b64 s[12:13], s[4:5], 10
	v_readlane_b32 s4, v2, 10
	global_load_dwordx4 v[28:31], v[0:1], off
	v_lshl_add_u64 v[0:1], v[66:67], 0, s[12:13]
	s_lshl_b64 s[12:13], s[4:5], 10
	v_readlane_b32 s4, v2, 11
	global_load_dwordx4 v[24:27], v[0:1], off
	v_lshl_add_u64 v[0:1], v[66:67], 0, s[12:13]
	s_lshl_b64 s[12:13], s[4:5], 10
	v_readlane_b32 s4, v2, 12
	global_load_dwordx4 v[20:23], v[0:1], off
	v_lshl_add_u64 v[0:1], v[66:67], 0, s[12:13]
	s_lshl_b64 s[12:13], s[4:5], 10
	v_readlane_b32 s4, v2, 13
	global_load_dwordx4 v[16:19], v[0:1], off
	v_lshl_add_u64 v[0:1], v[66:67], 0, s[12:13]
	s_lshl_b64 s[12:13], s[4:5], 10
	v_readlane_b32 s4, v2, 14
	global_load_dwordx4 v[12:15], v[0:1], off
	v_lshl_add_u64 v[0:1], v[66:67], 0, s[12:13]
	s_lshl_b64 s[12:13], s[4:5], 10
	v_readlane_b32 s4, v2, 15
	global_load_dwordx4 v[8:11], v[0:1], off
	v_lshl_add_u64 v[0:1], v[66:67], 0, s[12:13]
	s_lshl_b64 s[12:13], s[4:5], 10
	s_waitcnt vmcnt(14)
	v_readlane_b32 s4, v68, 0
	s_waitcnt lgkmcnt(0)
	global_load_dwordx4 v[4:7], v[0:1], off
	v_lshl_add_u64 v[0:1], v[66:67], 0, s[12:13]
	global_load_dwordx4 v[0:3], v[0:1], off
	s_add_u32 s0, s0, 32
	s_addc_u32 s1, s1, 0
	s_cmpk_lg_i32 s0, 0x100
	s_waitcnt vmcnt(15)
	v_cvt_scalef32_pk_f32_fp4 v[114:115], v60, 1.0
	v_pk_fma_f32 v[110:111], v[114:115], s[4:5], v[110:111] op_sel_hi:[1,0,1]
	v_cvt_scalef32_pk_f32_fp4 v[114:115], v60, 1.0 op_sel:[1,0,0]
	v_pk_fma_f32 v[108:109], s[4:5], v[114:115], v[108:109] op_sel_hi:[0,1,1]
	v_cvt_scalef32_pk_f32_fp4 v[114:115], v60, 1.0 op_sel:[0,1,0]
	v_pk_fma_f32 v[106:107], s[4:5], v[114:115], v[106:107] op_sel_hi:[0,1,1]
	v_cvt_scalef32_pk_f32_fp4 v[114:115], v60, 1.0 op_sel:[1,1,0]
	v_pk_fma_f32 v[104:105], s[4:5], v[114:115], v[104:105] op_sel_hi:[0,1,1]
	v_cvt_scalef32_pk_f32_fp4 v[114:115], v61, 1.0
	v_pk_fma_f32 v[102:103], s[4:5], v[114:115], v[102:103] op_sel_hi:[0,1,1]
	v_cvt_scalef32_pk_f32_fp4 v[114:115], v61, 1.0 op_sel:[1,0,0]
	v_pk_fma_f32 v[100:101], s[4:5], v[114:115], v[100:101] op_sel_hi:[0,1,1]
	v_cvt_scalef32_pk_f32_fp4 v[114:115], v61, 1.0 op_sel:[0,1,0]
	v_cvt_scalef32_pk_f32_fp4 v[60:61], v61, 1.0 op_sel:[1,1,0]
	v_pk_fma_f32 v[60:61], s[4:5], v[60:61], v[96:97] op_sel_hi:[0,1,1]
	v_cvt_scalef32_pk_f32_fp4 v[96:97], v62, 1.0
	v_pk_fma_f32 v[94:95], s[4:5], v[96:97], v[94:95] op_sel_hi:[0,1,1]
	v_cvt_scalef32_pk_f32_fp4 v[96:97], v62, 1.0 op_sel:[1,0,0]
	v_pk_fma_f32 v[92:93], s[4:5], v[96:97], v[92:93] op_sel_hi:[0,1,1]
	v_cvt_scalef32_pk_f32_fp4 v[96:97], v62, 1.0 op_sel:[0,1,0]
	v_pk_fma_f32 v[90:91], s[4:5], v[96:97], v[90:91] op_sel_hi:[0,1,1]
	v_cvt_scalef32_pk_f32_fp4 v[96:97], v62, 1.0 op_sel:[1,1,0]
	v_pk_fma_f32 v[88:89], s[4:5], v[96:97], v[88:89] op_sel_hi:[0,1,1]
	v_cvt_scalef32_pk_f32_fp4 v[96:97], v63, 1.0
	v_pk_fma_f32 v[86:87], s[4:5], v[96:97], v[86:87] op_sel_hi:[0,1,1]
	v_cvt_scalef32_pk_f32_fp4 v[96:97], v63, 1.0 op_sel:[1,0,0]
	v_pk_fma_f32 v[84:85], s[4:5], v[96:97], v[84:85] op_sel_hi:[0,1,1]
	v_cvt_scalef32_pk_f32_fp4 v[96:97], v63, 1.0 op_sel:[0,1,0]
	v_cvt_scalef32_pk_f32_fp4 v[62:63], v63, 1.0 op_sel:[1,1,0]
	v_pk_fma_f32 v[98:99], s[4:5], v[114:115], v[98:99] op_sel_hi:[0,1,1]
	v_pk_fma_f32 v[82:83], s[4:5], v[96:97], v[82:83] op_sel_hi:[0,1,1]
	v_pk_fma_f32 v[62:63], s[4:5], v[62:63], v[80:81] op_sel_hi:[0,1,1]
	v_readlane_b32 s4, v68, 1
	s_waitcnt vmcnt(14)
	v_cvt_scalef32_pk_f32_fp4 v[96:97], v56, 1.0 op_sel:[1,0,0]
	v_pk_fma_f32 v[96:97], s[4:5], v[96:97], v[108:109] op_sel_hi:[0,1,1]
	v_cvt_scalef32_pk_f32_fp4 v[108:109], v56, 1.0 op_sel:[0,1,0]
	v_pk_fma_f32 v[106:107], s[4:5], v[108:109], v[106:107] op_sel_hi:[0,1,1]
	v_cvt_scalef32_pk_f32_fp4 v[108:109], v56, 1.0 op_sel:[1,1,0]
	v_pk_fma_f32 v[104:105], s[4:5], v[108:109], v[104:105] op_sel_hi:[0,1,1]
	v_cvt_scalef32_pk_f32_fp4 v[108:109], v57, 1.0
	v_pk_fma_f32 v[102:103], s[4:5], v[108:109], v[102:103] op_sel_hi:[0,1,1]
	v_cvt_scalef32_pk_f32_fp4 v[108:109], v57, 1.0 op_sel:[1,0,0]
	v_cvt_scalef32_pk_f32_fp4 v[80:81], v56, 1.0
	v_pk_fma_f32 v[100:101], s[4:5], v[108:109], v[100:101] op_sel_hi:[0,1,1]
	v_cvt_scalef32_pk_f32_fp4 v[108:109], v57, 1.0 op_sel:[0,1,0]
	v_cvt_scalef32_pk_f32_fp4 v[56:57], v57, 1.0 op_sel:[1,1,0]
	v_pk_fma_f32 v[56:57], s[4:5], v[56:57], v[60:61] op_sel_hi:[0,1,1]
	v_cvt_scalef32_pk_f32_fp4 v[60:61], v58, 1.0
	v_pk_fma_f32 v[60:61], s[4:5], v[60:61], v[94:95] op_sel_hi:[0,1,1]
	v_cvt_scalef32_pk_f32_fp4 v[94:95], v58, 1.0 op_sel:[1,0,0]
	v_pk_fma_f32 v[92:93], s[4:5], v[94:95], v[92:93] op_sel_hi:[0,1,1]
	v_cvt_scalef32_pk_f32_fp4 v[94:95], v58, 1.0 op_sel:[0,1,0]
	v_pk_fma_f32 v[90:91], s[4:5], v[94:95], v[90:91] op_sel_hi:[0,1,1]
	v_cvt_scalef32_pk_f32_fp4 v[94:95], v58, 1.0 op_sel:[1,1,0]
	v_pk_fma_f32 v[88:89], s[4:5], v[94:95], v[88:89] op_sel_hi:[0,1,1]
	v_cvt_scalef32_pk_f32_fp4 v[94:95], v59, 1.0
	v_pk_fma_f32 v[86:87], s[4:5], v[94:95], v[86:87] op_sel_hi:[0,1,1]
	v_cvt_scalef32_pk_f32_fp4 v[94:95], v59, 1.0 op_sel:[1,0,0]
	v_pk_fma_f32 v[80:81], v[80:81], s[4:5], v[110:111] op_sel_hi:[1,0,1]
	v_pk_fma_f32 v[84:85], s[4:5], v[94:95], v[84:85] op_sel_hi:[0,1,1]
	v_cvt_scalef32_pk_f32_fp4 v[94:95], v59, 1.0 op_sel:[0,1,0]
	v_cvt_scalef32_pk_f32_fp4 v[58:59], v59, 1.0 op_sel:[1,1,0]
	v_pk_fma_f32 v[98:99], s[4:5], v[108:109], v[98:99] op_sel_hi:[0,1,1]
	v_pk_fma_f32 v[82:83], s[4:5], v[94:95], v[82:83] op_sel_hi:[0,1,1]
	v_pk_fma_f32 v[58:59], s[4:5], v[58:59], v[62:63] op_sel_hi:[0,1,1]
	v_readlane_b32 s4, v68, 2
	s_waitcnt vmcnt(13)
	v_cvt_scalef32_pk_f32_fp4 v[94:95], v52, 1.0 op_sel:[0,1,0]
	v_cvt_scalef32_pk_f32_fp4 v[62:63], v52, 1.0
	v_pk_fma_f32 v[106:107], s[4:5], v[94:95], v[106:107] op_sel_hi:[0,1,1]
	v_cvt_scalef32_pk_f32_fp4 v[94:95], v52, 1.0 op_sel:[1,1,0]
	v_pk_fma_f32 v[104:105], s[4:5], v[94:95], v[104:105] op_sel_hi:[0,1,1]
	v_cvt_scalef32_pk_f32_fp4 v[94:95], v53, 1.0
	v_pk_fma_f32 v[102:103], s[4:5], v[94:95], v[102:103] op_sel_hi:[0,1,1]
	v_cvt_scalef32_pk_f32_fp4 v[94:95], v53, 1.0 op_sel:[1,0,0]
	v_pk_fma_f32 v[62:63], v[62:63], s[4:5], v[80:81] op_sel_hi:[1,0,1]
	v_cvt_scalef32_pk_f32_fp4 v[80:81], v52, 1.0 op_sel:[1,0,0]
	v_pk_fma_f32 v[100:101], s[4:5], v[94:95], v[100:101] op_sel_hi:[0,1,1]
	v_cvt_scalef32_pk_f32_fp4 v[94:95], v53, 1.0 op_sel:[0,1,0]
	v_cvt_scalef32_pk_f32_fp4 v[52:53], v53, 1.0 op_sel:[1,1,0]
	v_pk_fma_f32 v[52:53], s[4:5], v[52:53], v[56:57] op_sel_hi:[0,1,1]
	v_cvt_scalef32_pk_f32_fp4 v[56:57], v54, 1.0
	v_pk_fma_f32 v[56:57], s[4:5], v[56:57], v[60:61] op_sel_hi:[0,1,1]
	v_cvt_scalef32_pk_f32_fp4 v[60:61], v54, 1.0 op_sel:[1,0,0]
	v_pk_fma_f32 v[60:61], s[4:5], v[60:61], v[92:93] op_sel_hi:[0,1,1]
	v_cvt_scalef32_pk_f32_fp4 v[92:93], v54, 1.0 op_sel:[0,1,0]
	v_pk_fma_f32 v[108:109], s[4:5], v[92:93], v[90:91] op_sel_hi:[0,1,1]
	v_cvt_scalef32_pk_f32_fp4 v[90:91], v54, 1.0 op_sel:[1,1,0]
	v_pk_fma_f32 v[110:111], s[4:5], v[90:91], v[88:89] op_sel_hi:[0,1,1]
	v_cvt_scalef32_pk_f32_fp4 v[88:89], v55, 1.0
	v_pk_fma_f32 v[114:115], s[4:5], v[88:89], v[86:87] op_sel_hi:[0,1,1]
	v_cvt_scalef32_pk_f32_fp4 v[86:87], v55, 1.0 op_sel:[1,0,0]
	v_pk_fma_f32 v[116:117], s[4:5], v[86:87], v[84:85] op_sel_hi:[0,1,1]
	v_cvt_scalef32_pk_f32_fp4 v[84:85], v55, 1.0 op_sel:[0,1,0]
	v_cvt_scalef32_pk_f32_fp4 v[54:55], v55, 1.0 op_sel:[1,1,0]
	v_pk_fma_f32 v[80:81], s[4:5], v[80:81], v[96:97] op_sel_hi:[0,1,1]
	v_pk_fma_f32 v[98:99], s[4:5], v[94:95], v[98:99] op_sel_hi:[0,1,1]
	v_pk_fma_f32 v[118:119], s[4:5], v[84:85], v[82:83] op_sel_hi:[0,1,1]
	v_pk_fma_f32 v[120:121], s[4:5], v[54:55], v[58:59] op_sel_hi:[0,1,1]
	v_readlane_b32 s4, v68, 3
	s_waitcnt vmcnt(12)
	v_cvt_scalef32_pk_f32_fp4 v[54:55], v48, 1.0
	s_nop 0
	v_pk_fma_f32 v[96:97], v[54:55], s[4:5], v[62:63] op_sel_hi:[1,0,1]
	v_cvt_scalef32_pk_f32_fp4 v[54:55], v48, 1.0 op_sel:[1,0,0]
	v_pk_fma_f32 v[94:95], s[4:5], v[54:55], v[80:81] op_sel_hi:[0,1,1]
	v_cvt_scalef32_pk_f32_fp4 v[54:55], v48, 1.0 op_sel:[0,1,0]
	v_pk_fma_f32 v[92:93], s[4:5], v[54:55], v[106:107] op_sel_hi:[0,1,1]
	v_cvt_scalef32_pk_f32_fp4 v[54:55], v48, 1.0 op_sel:[1,1,0]
	v_pk_fma_f32 v[90:91], s[4:5], v[54:55], v[104:105] op_sel_hi:[0,1,1]
	v_cvt_scalef32_pk_f32_fp4 v[54:55], v49, 1.0
	v_pk_fma_f32 v[88:89], s[4:5], v[54:55], v[102:103] op_sel_hi:[0,1,1]
	v_cvt_scalef32_pk_f32_fp4 v[54:55], v49, 1.0 op_sel:[1,0,0]
	v_pk_fma_f32 v[86:87], s[4:5], v[54:55], v[100:101] op_sel_hi:[0,1,1]
	v_cvt_scalef32_pk_f32_fp4 v[54:55], v49, 1.0 op_sel:[0,1,0]
	v_cvt_scalef32_pk_f32_fp4 v[48:49], v49, 1.0 op_sel:[1,1,0]
	s_nop 0
	v_pk_fma_f32 v[82:83], s[4:5], v[48:49], v[52:53] op_sel_hi:[0,1,1]
	v_cvt_scalef32_pk_f32_fp4 v[48:49], v50, 1.0
	v_pk_fma_f32 v[80:81], s[4:5], v[48:49], v[56:57] op_sel_hi:[0,1,1]
	v_cvt_scalef32_pk_f32_fp4 v[48:49], v50, 1.0 op_sel:[1,0,0]
	v_pk_fma_f32 v[62:63], s[4:5], v[48:49], v[60:61] op_sel_hi:[0,1,1]
	v_cvt_scalef32_pk_f32_fp4 v[48:49], v50, 1.0 op_sel:[0,1,0]
	v_pk_fma_f32 v[60:61], s[4:5], v[48:49], v[108:109] op_sel_hi:[0,1,1]
	v_cvt_scalef32_pk_f32_fp4 v[48:49], v50, 1.0 op_sel:[1,1,0]
	v_pk_fma_f32 v[58:59], s[4:5], v[48:49], v[110:111] op_sel_hi:[0,1,1]
	v_cvt_scalef32_pk_f32_fp4 v[48:49], v51, 1.0
	v_pk_fma_f32 v[56:57], s[4:5], v[48:49], v[114:115] op_sel_hi:[0,1,1]
	v_cvt_scalef32_pk_f32_fp4 v[48:49], v51, 1.0 op_sel:[1,0,0]
	v_pk_fma_f32 v[84:85], s[4:5], v[54:55], v[98:99] op_sel_hi:[0,1,1]
	v_pk_fma_f32 v[54:55], s[4:5], v[48:49], v[116:117] op_sel_hi:[0,1,1]
	v_cvt_scalef32_pk_f32_fp4 v[48:49], v51, 1.0 op_sel:[0,1,0]
	s_nop 0
	v_pk_fma_f32 v[52:53], s[4:5], v[48:49], v[118:119] op_sel_hi:[0,1,1]
	v_cvt_scalef32_pk_f32_fp4 v[48:49], v51, 1.0 op_sel:[1,1,0]
	v_pk_fma_f32 v[48:49], s[4:5], v[48:49], v[120:121] op_sel_hi:[0,1,1]
	v_readlane_b32 s4, v68, 4
	s_waitcnt vmcnt(11)
	v_cvt_scalef32_pk_f32_fp4 v[50:51], v44, 1.0
	v_pk_fma_f32 v[50:51], v[50:51], s[4:5], v[96:97] op_sel_hi:[1,0,1]
	v_cvt_scalef32_pk_f32_fp4 v[96:97], v44, 1.0 op_sel:[1,0,0]
	v_pk_fma_f32 v[94:95], s[4:5], v[96:97], v[94:95] op_sel_hi:[0,1,1]
	v_cvt_scalef32_pk_f32_fp4 v[96:97], v44, 1.0 op_sel:[0,1,0]
	v_pk_fma_f32 v[92:93], s[4:5], v[96:97], v[92:93] op_sel_hi:[0,1,1]
	v_cvt_scalef32_pk_f32_fp4 v[96:97], v44, 1.0 op_sel:[1,1,0]
	v_pk_fma_f32 v[90:91], s[4:5], v[96:97], v[90:91] op_sel_hi:[0,1,1]
	v_cvt_scalef32_pk_f32_fp4 v[96:97], v45, 1.0
	v_pk_fma_f32 v[88:89], s[4:5], v[96:97], v[88:89] op_sel_hi:[0,1,1]
	v_cvt_scalef32_pk_f32_fp4 v[96:97], v45, 1.0 op_sel:[1,0,0]
	v_pk_fma_f32 v[86:87], s[4:5], v[96:97], v[86:87] op_sel_hi:[0,1,1]
	v_cvt_scalef32_pk_f32_fp4 v[96:97], v45, 1.0 op_sel:[0,1,0]
	v_cvt_scalef32_pk_f32_fp4 v[44:45], v45, 1.0 op_sel:[1,1,0]
	v_pk_fma_f32 v[44:45], s[4:5], v[44:45], v[82:83] op_sel_hi:[0,1,1]
	v_cvt_scalef32_pk_f32_fp4 v[82:83], v46, 1.0
	v_pk_fma_f32 v[80:81], s[4:5], v[82:83], v[80:81] op_sel_hi:[0,1,1]
	v_cvt_scalef32_pk_f32_fp4 v[82:83], v46, 1.0 op_sel:[1,0,0]
	v_pk_fma_f32 v[62:63], s[4:5], v[82:83], v[62:63] op_sel_hi:[0,1,1]
	v_cvt_scalef32_pk_f32_fp4 v[82:83], v46, 1.0 op_sel:[0,1,0]
	v_pk_fma_f32 v[60:61], s[4:5], v[82:83], v[60:61] op_sel_hi:[0,1,1]
	v_cvt_scalef32_pk_f32_fp4 v[82:83], v46, 1.0 op_sel:[1,1,0]
	v_pk_fma_f32 v[58:59], s[4:5], v[82:83], v[58:59] op_sel_hi:[0,1,1]
	v_cvt_scalef32_pk_f32_fp4 v[82:83], v47, 1.0
	v_pk_fma_f32 v[56:57], s[4:5], v[82:83], v[56:57] op_sel_hi:[0,1,1]
	v_cvt_scalef32_pk_f32_fp4 v[82:83], v47, 1.0 op_sel:[1,0,0]
	v_pk_fma_f32 v[54:55], s[4:5], v[82:83], v[54:55] op_sel_hi:[0,1,1]
	v_cvt_scalef32_pk_f32_fp4 v[82:83], v47, 1.0 op_sel:[0,1,0]
	v_cvt_scalef32_pk_f32_fp4 v[46:47], v47, 1.0 op_sel:[1,1,0]
	v_pk_fma_f32 v[84:85], s[4:5], v[96:97], v[84:85] op_sel_hi:[0,1,1]
	v_pk_fma_f32 v[52:53], s[4:5], v[82:83], v[52:53] op_sel_hi:[0,1,1]
	v_pk_fma_f32 v[46:47], s[4:5], v[46:47], v[48:49] op_sel_hi:[0,1,1]
	v_readlane_b32 s4, v68, 5
	s_waitcnt vmcnt(10)
	v_cvt_scalef32_pk_f32_fp4 v[82:83], v40, 1.0 op_sel:[0,1,0]
	v_cvt_scalef32_pk_f32_fp4 v[48:49], v40, 1.0
	v_pk_fma_f32 v[82:83], s[4:5], v[82:83], v[92:93] op_sel_hi:[0,1,1]
	v_cvt_scalef32_pk_f32_fp4 v[92:93], v40, 1.0 op_sel:[1,1,0]
	v_pk_fma_f32 v[90:91], s[4:5], v[92:93], v[90:91] op_sel_hi:[0,1,1]
	v_cvt_scalef32_pk_f32_fp4 v[92:93], v41, 1.0
	v_pk_fma_f32 v[88:89], s[4:5], v[92:93], v[88:89] op_sel_hi:[0,1,1]
	v_cvt_scalef32_pk_f32_fp4 v[92:93], v41, 1.0 op_sel:[1,0,0]
	v_pk_fma_f32 v[48:49], v[48:49], s[4:5], v[50:51] op_sel_hi:[1,0,1]
	v_cvt_scalef32_pk_f32_fp4 v[50:51], v40, 1.0 op_sel:[1,0,0]
	v_pk_fma_f32 v[86:87], s[4:5], v[92:93], v[86:87] op_sel_hi:[0,1,1]
	v_cvt_scalef32_pk_f32_fp4 v[92:93], v41, 1.0 op_sel:[0,1,0]
	v_cvt_scalef32_pk_f32_fp4 v[40:41], v41, 1.0 op_sel:[1,1,0]
	v_pk_fma_f32 v[40:41], s[4:5], v[40:41], v[44:45] op_sel_hi:[0,1,1]
	v_cvt_scalef32_pk_f32_fp4 v[44:45], v42, 1.0
	v_pk_fma_f32 v[44:45], s[4:5], v[44:45], v[80:81] op_sel_hi:[0,1,1]
	v_cvt_scalef32_pk_f32_fp4 v[80:81], v42, 1.0 op_sel:[1,0,0]
	v_pk_fma_f32 v[62:63], s[4:5], v[80:81], v[62:63] op_sel_hi:[0,1,1]
	v_cvt_scalef32_pk_f32_fp4 v[80:81], v42, 1.0 op_sel:[0,1,0]
	v_pk_fma_f32 v[60:61], s[4:5], v[80:81], v[60:61] op_sel_hi:[0,1,1]
	v_cvt_scalef32_pk_f32_fp4 v[80:81], v42, 1.0 op_sel:[1,1,0]
	v_pk_fma_f32 v[58:59], s[4:5], v[80:81], v[58:59] op_sel_hi:[0,1,1]
	v_cvt_scalef32_pk_f32_fp4 v[80:81], v43, 1.0
	v_pk_fma_f32 v[56:57], s[4:5], v[80:81], v[56:57] op_sel_hi:[0,1,1]
	v_cvt_scalef32_pk_f32_fp4 v[80:81], v43, 1.0 op_sel:[1,0,0]
	v_pk_fma_f32 v[54:55], s[4:5], v[80:81], v[54:55] op_sel_hi:[0,1,1]
	v_cvt_scalef32_pk_f32_fp4 v[80:81], v43, 1.0 op_sel:[0,1,0]
	v_cvt_scalef32_pk_f32_fp4 v[42:43], v43, 1.0 op_sel:[1,1,0]
	v_pk_fma_f32 v[50:51], s[4:5], v[50:51], v[94:95] op_sel_hi:[0,1,1]
	v_pk_fma_f32 v[84:85], s[4:5], v[92:93], v[84:85] op_sel_hi:[0,1,1]
	v_pk_fma_f32 v[52:53], s[4:5], v[80:81], v[52:53] op_sel_hi:[0,1,1]
	v_pk_fma_f32 v[42:43], s[4:5], v[42:43], v[46:47] op_sel_hi:[0,1,1]
	v_readlane_b32 s4, v68, 6
	s_waitcnt vmcnt(9)
	v_cvt_scalef32_pk_f32_fp4 v[46:47], v36, 1.0
	v_pk_fma_f32 v[46:47], v[46:47], s[4:5], v[48:49] op_sel_hi:[1,0,1]
	v_cvt_scalef32_pk_f32_fp4 v[48:49], v36, 1.0 op_sel:[1,0,0]
	v_pk_fma_f32 v[48:49], s[4:5], v[48:49], v[50:51] op_sel_hi:[0,1,1]
	v_cvt_scalef32_pk_f32_fp4 v[50:51], v36, 1.0 op_sel:[0,1,0]
	v_pk_fma_f32 v[50:51], s[4:5], v[50:51], v[82:83] op_sel_hi:[0,1,1]
	v_cvt_scalef32_pk_f32_fp4 v[82:83], v37, 1.0
	v_pk_fma_f32 v[82:83], s[4:5], v[82:83], v[88:89] op_sel_hi:[0,1,1]
	v_cvt_scalef32_pk_f32_fp4 v[88:89], v37, 1.0 op_sel:[1,0,0]
	v_cvt_scalef32_pk_f32_fp4 v[80:81], v36, 1.0 op_sel:[1,1,0]
	v_pk_fma_f32 v[86:87], s[4:5], v[88:89], v[86:87] op_sel_hi:[0,1,1]
	v_cvt_scalef32_pk_f32_fp4 v[88:89], v37, 1.0 op_sel:[0,1,0]
	v_cvt_scalef32_pk_f32_fp4 v[36:37], v37, 1.0 op_sel:[1,1,0]
	v_pk_fma_f32 v[36:37], s[4:5], v[36:37], v[40:41] op_sel_hi:[0,1,1]
	v_cvt_scalef32_pk_f32_fp4 v[40:41], v38, 1.0
	v_pk_fma_f32 v[40:41], s[4:5], v[40:41], v[44:45] op_sel_hi:[0,1,1]
	v_cvt_scalef32_pk_f32_fp4 v[44:45], v38, 1.0 op_sel:[1,0,0]
	v_pk_fma_f32 v[44:45], s[4:5], v[44:45], v[62:63] op_sel_hi:[0,1,1]
	v_cvt_scalef32_pk_f32_fp4 v[62:63], v38, 1.0 op_sel:[0,1,0]
	v_pk_fma_f32 v[60:61], s[4:5], v[62:63], v[60:61] op_sel_hi:[0,1,1]
	v_cvt_scalef32_pk_f32_fp4 v[62:63], v38, 1.0 op_sel:[1,1,0]
	v_pk_fma_f32 v[58:59], s[4:5], v[62:63], v[58:59] op_sel_hi:[0,1,1]
	v_cvt_scalef32_pk_f32_fp4 v[62:63], v39, 1.0
	v_pk_fma_f32 v[56:57], s[4:5], v[62:63], v[56:57] op_sel_hi:[0,1,1]
	v_cvt_scalef32_pk_f32_fp4 v[62:63], v39, 1.0 op_sel:[1,0,0]
	v_pk_fma_f32 v[54:55], s[4:5], v[62:63], v[54:55] op_sel_hi:[0,1,1]
	v_cvt_scalef32_pk_f32_fp4 v[62:63], v39, 1.0 op_sel:[0,1,0]
	v_cvt_scalef32_pk_f32_fp4 v[38:39], v39, 1.0 op_sel:[1,1,0]
	v_pk_fma_f32 v[80:81], s[4:5], v[80:81], v[90:91] op_sel_hi:[0,1,1]
	v_pk_fma_f32 v[84:85], s[4:5], v[88:89], v[84:85] op_sel_hi:[0,1,1]
	v_pk_fma_f32 v[52:53], s[4:5], v[62:63], v[52:53] op_sel_hi:[0,1,1]
	v_pk_fma_f32 v[38:39], s[4:5], v[38:39], v[42:43] op_sel_hi:[0,1,1]
	v_readlane_b32 s4, v68, 7
	s_waitcnt vmcnt(8)
	v_cvt_scalef32_pk_f32_fp4 v[42:43], v32, 1.0
	v_pk_fma_f32 v[42:43], v[42:43], s[4:5], v[46:47] op_sel_hi:[1,0,1]
	v_cvt_scalef32_pk_f32_fp4 v[46:47], v32, 1.0 op_sel:[1,0,0]
	v_pk_fma_f32 v[46:47], s[4:5], v[46:47], v[48:49] op_sel_hi:[0,1,1]
	v_cvt_scalef32_pk_f32_fp4 v[48:49], v32, 1.0 op_sel:[0,1,0]
	v_pk_fma_f32 v[48:49], s[4:5], v[48:49], v[50:51] op_sel_hi:[0,1,1]
	v_cvt_scalef32_pk_f32_fp4 v[50:51], v32, 1.0 op_sel:[1,1,0]
	v_cvt_scalef32_pk_f32_fp4 v[62:63], v33, 1.0
	v_pk_fma_f32 v[50:51], s[4:5], v[50:51], v[80:81] op_sel_hi:[0,1,1]
	v_pk_fma_f32 v[62:63], s[4:5], v[62:63], v[82:83] op_sel_hi:[0,1,1]
	v_cvt_scalef32_pk_f32_fp4 v[80:81], v33, 1.0 op_sel:[1,0,0]
	v_cvt_scalef32_pk_f32_fp4 v[82:83], v33, 1.0 op_sel:[0,1,0]
	v_cvt_scalef32_pk_f32_fp4 v[32:33], v33, 1.0 op_sel:[1,1,0]
	v_pk_fma_f32 v[32:33], s[4:5], v[32:33], v[36:37] op_sel_hi:[0,1,1]
	v_cvt_scalef32_pk_f32_fp4 v[36:37], v34, 1.0
	v_pk_fma_f32 v[36:37], s[4:5], v[36:37], v[40:41] op_sel_hi:[0,1,1]
	v_cvt_scalef32_pk_f32_fp4 v[40:41], v34, 1.0 op_sel:[1,0,0]
	v_pk_fma_f32 v[40:41], s[4:5], v[40:41], v[44:45] op_sel_hi:[0,1,1]
	v_cvt_scalef32_pk_f32_fp4 v[44:45], v34, 1.0 op_sel:[0,1,0]
	v_pk_fma_f32 v[44:45], s[4:5], v[44:45], v[60:61] op_sel_hi:[0,1,1]
	v_cvt_scalef32_pk_f32_fp4 v[60:61], v34, 1.0 op_sel:[1,1,0]
	v_pk_fma_f32 v[58:59], s[4:5], v[60:61], v[58:59] op_sel_hi:[0,1,1]
	v_cvt_scalef32_pk_f32_fp4 v[60:61], v35, 1.0
	v_pk_fma_f32 v[56:57], s[4:5], v[60:61], v[56:57] op_sel_hi:[0,1,1]
	v_cvt_scalef32_pk_f32_fp4 v[60:61], v35, 1.0 op_sel:[1,0,0]
	v_pk_fma_f32 v[54:55], s[4:5], v[60:61], v[54:55] op_sel_hi:[0,1,1]
	v_cvt_scalef32_pk_f32_fp4 v[60:61], v35, 1.0 op_sel:[0,1,0]
	v_cvt_scalef32_pk_f32_fp4 v[34:35], v35, 1.0 op_sel:[1,1,0]
	v_pk_fma_f32 v[80:81], s[4:5], v[80:81], v[86:87] op_sel_hi:[0,1,1]
	v_pk_fma_f32 v[82:83], s[4:5], v[82:83], v[84:85] op_sel_hi:[0,1,1]
	v_pk_fma_f32 v[52:53], s[4:5], v[60:61], v[52:53] op_sel_hi:[0,1,1]
	v_pk_fma_f32 v[34:35], s[4:5], v[34:35], v[38:39] op_sel_hi:[0,1,1]
	v_readlane_b32 s4, v68, 8
	s_waitcnt vmcnt(7)
	v_cvt_scalef32_pk_f32_fp4 v[38:39], v28, 1.0
	v_pk_fma_f32 v[38:39], v[38:39], s[4:5], v[42:43] op_sel_hi:[1,0,1]
	v_cvt_scalef32_pk_f32_fp4 v[42:43], v28, 1.0 op_sel:[1,0,0]
	v_pk_fma_f32 v[42:43], v[42:43], s[4:5], v[46:47] op_sel_hi:[1,0,1]
	v_cvt_scalef32_pk_f32_fp4 v[46:47], v28, 1.0 op_sel:[0,1,0]
	v_pk_fma_f32 v[46:47], s[4:5], v[46:47], v[48:49] op_sel_hi:[0,1,1]
	v_cvt_scalef32_pk_f32_fp4 v[48:49], v28, 1.0 op_sel:[1,1,0]
	v_pk_fma_f32 v[48:49], s[4:5], v[48:49], v[50:51] op_sel_hi:[0,1,1]
	v_cvt_scalef32_pk_f32_fp4 v[50:51], v29, 1.0
	v_pk_fma_f32 v[50:51], s[4:5], v[50:51], v[62:63] op_sel_hi:[0,1,1]
	v_cvt_scalef32_pk_f32_fp4 v[60:61], v29, 1.0 op_sel:[1,0,0]
	v_cvt_scalef32_pk_f32_fp4 v[62:63], v29, 1.0 op_sel:[0,1,0]
	v_cvt_scalef32_pk_f32_fp4 v[28:29], v29, 1.0 op_sel:[1,1,0]
	v_pk_fma_f32 v[28:29], s[4:5], v[28:29], v[32:33] op_sel_hi:[0,1,1]
	v_cvt_scalef32_pk_f32_fp4 v[32:33], v30, 1.0
	v_pk_fma_f32 v[32:33], s[4:5], v[32:33], v[36:37] op_sel_hi:[0,1,1]
	v_cvt_scalef32_pk_f32_fp4 v[36:37], v30, 1.0 op_sel:[1,0,0]
	v_pk_fma_f32 v[36:37], s[4:5], v[36:37], v[40:41] op_sel_hi:[0,1,1]
	v_cvt_scalef32_pk_f32_fp4 v[40:41], v30, 1.0 op_sel:[0,1,0]
	v_pk_fma_f32 v[40:41], s[4:5], v[40:41], v[44:45] op_sel_hi:[0,1,1]
	v_cvt_scalef32_pk_f32_fp4 v[44:45], v30, 1.0 op_sel:[1,1,0]
	v_pk_fma_f32 v[44:45], s[4:5], v[44:45], v[58:59] op_sel_hi:[0,1,1]
	v_cvt_scalef32_pk_f32_fp4 v[58:59], v31, 1.0
	v_pk_fma_f32 v[56:57], s[4:5], v[58:59], v[56:57] op_sel_hi:[0,1,1]
	v_cvt_scalef32_pk_f32_fp4 v[58:59], v31, 1.0 op_sel:[1,0,0]
	v_pk_fma_f32 v[54:55], s[4:5], v[58:59], v[54:55] op_sel_hi:[0,1,1]
	v_cvt_scalef32_pk_f32_fp4 v[58:59], v31, 1.0 op_sel:[0,1,0]
	v_cvt_scalef32_pk_f32_fp4 v[30:31], v31, 1.0 op_sel:[1,1,0]
	v_pk_fma_f32 v[60:61], s[4:5], v[60:61], v[80:81] op_sel_hi:[0,1,1]
	v_pk_fma_f32 v[62:63], s[4:5], v[62:63], v[82:83] op_sel_hi:[0,1,1]
	v_pk_fma_f32 v[52:53], s[4:5], v[58:59], v[52:53] op_sel_hi:[0,1,1]
	v_pk_fma_f32 v[30:31], s[4:5], v[30:31], v[34:35] op_sel_hi:[0,1,1]
	v_readlane_b32 s4, v68, 9
	s_waitcnt vmcnt(6)
	v_cvt_scalef32_pk_f32_fp4 v[34:35], v24, 1.0
	v_pk_fma_f32 v[34:35], v[34:35], s[4:5], v[38:39] op_sel_hi:[1,0,1]
	v_cvt_scalef32_pk_f32_fp4 v[38:39], v24, 1.0 op_sel:[1,0,0]
	v_pk_fma_f32 v[38:39], v[38:39], s[4:5], v[42:43] op_sel_hi:[1,0,1]
	v_cvt_scalef32_pk_f32_fp4 v[42:43], v24, 1.0 op_sel:[0,1,0]
	v_pk_fma_f32 v[42:43], s[4:5], v[42:43], v[46:47] op_sel_hi:[0,1,1]
	v_cvt_scalef32_pk_f32_fp4 v[46:47], v24, 1.0 op_sel:[1,1,0]
	v_pk_fma_f32 v[46:47], s[4:5], v[46:47], v[48:49] op_sel_hi:[0,1,1]
	v_cvt_scalef32_pk_f32_fp4 v[48:49], v25, 1.0
	v_pk_fma_f32 v[48:49], s[4:5], v[48:49], v[50:51] op_sel_hi:[0,1,1]
	v_cvt_scalef32_pk_f32_fp4 v[50:51], v25, 1.0 op_sel:[1,0,0]
	v_cvt_scalef32_pk_f32_fp4 v[58:59], v25, 1.0 op_sel:[0,1,0]
	v_cvt_scalef32_pk_f32_fp4 v[24:25], v25, 1.0 op_sel:[1,1,0]
	v_pk_fma_f32 v[50:51], s[4:5], v[50:51], v[60:61] op_sel_hi:[0,1,1]
	v_pk_fma_f32 v[60:61], s[4:5], v[24:25], v[28:29] op_sel_hi:[0,1,1]
	v_cvt_scalef32_pk_f32_fp4 v[24:25], v26, 1.0
	v_pk_fma_f32 v[58:59], s[4:5], v[58:59], v[62:63] op_sel_hi:[0,1,1]
	v_pk_fma_f32 v[62:63], s[4:5], v[24:25], v[32:33] op_sel_hi:[0,1,1]
	v_cvt_scalef32_pk_f32_fp4 v[24:25], v26, 1.0 op_sel:[1,0,0]
	s_nop 0
	v_pk_fma_f32 v[80:81], s[4:5], v[24:25], v[36:37] op_sel_hi:[0,1,1]
	v_cvt_scalef32_pk_f32_fp4 v[24:25], v26, 1.0 op_sel:[0,1,0]
	v_pk_fma_f32 v[82:83], s[4:5], v[24:25], v[40:41] op_sel_hi:[0,1,1]
	v_cvt_scalef32_pk_f32_fp4 v[24:25], v26, 1.0 op_sel:[1,1,0]
	v_pk_fma_f32 v[44:45], s[4:5], v[24:25], v[44:45] op_sel_hi:[0,1,1]
	v_cvt_scalef32_pk_f32_fp4 v[24:25], v27, 1.0
	v_pk_fma_f32 v[56:57], s[4:5], v[24:25], v[56:57] op_sel_hi:[0,1,1]
	v_cvt_scalef32_pk_f32_fp4 v[24:25], v27, 1.0 op_sel:[1,0,0]
	v_pk_fma_f32 v[54:55], s[4:5], v[24:25], v[54:55] op_sel_hi:[0,1,1]
	v_cvt_scalef32_pk_f32_fp4 v[24:25], v27, 1.0 op_sel:[0,1,0]
	v_pk_fma_f32 v[52:53], s[4:5], v[24:25], v[52:53] op_sel_hi:[0,1,1]
	v_cvt_scalef32_pk_f32_fp4 v[24:25], v27, 1.0 op_sel:[1,1,0]
	v_pk_fma_f32 v[84:85], s[4:5], v[24:25], v[30:31] op_sel_hi:[0,1,1]
	v_readlane_b32 s4, v68, 10
	s_waitcnt vmcnt(5)
	v_cvt_scalef32_pk_f32_fp4 v[24:25], v20, 1.0
	v_cvt_scalef32_pk_f32_fp4 v[30:31], v20, 1.0 op_sel:[1,1,0]
	v_pk_fma_f32 v[24:25], v[24:25], s[4:5], v[34:35] op_sel_hi:[1,0,1]
	v_cvt_scalef32_pk_f32_fp4 v[26:27], v20, 1.0 op_sel:[1,0,0]
	v_cvt_scalef32_pk_f32_fp4 v[28:29], v20, 1.0 op_sel:[0,1,0]
	v_pk_fma_f32 v[30:31], s[4:5], v[30:31], v[46:47] op_sel_hi:[0,1,1]
	v_cvt_scalef32_pk_f32_fp4 v[32:33], v21, 1.0
	v_cvt_scalef32_pk_f32_fp4 v[34:35], v21, 1.0 op_sel:[1,0,0]
	v_cvt_scalef32_pk_f32_fp4 v[46:47], v22, 1.0 op_sel:[1,1,0]
	v_pk_fma_f32 v[26:27], v[26:27], s[4:5], v[38:39] op_sel_hi:[1,0,1]
	v_pk_fma_f32 v[28:29], s[4:5], v[28:29], v[42:43] op_sel_hi:[0,1,1]
	v_pk_fma_f32 v[32:33], s[4:5], v[32:33], v[48:49] op_sel_hi:[0,1,1]
	v_pk_fma_f32 v[34:35], s[4:5], v[34:35], v[50:51] op_sel_hi:[0,1,1]
	v_cvt_scalef32_pk_f32_fp4 v[36:37], v21, 1.0 op_sel:[0,1,0]
	v_cvt_scalef32_pk_f32_fp4 v[20:21], v21, 1.0 op_sel:[1,1,0]
	v_cvt_scalef32_pk_f32_fp4 v[38:39], v22, 1.0
	v_cvt_scalef32_pk_f32_fp4 v[40:41], v22, 1.0 op_sel:[1,0,0]
	v_cvt_scalef32_pk_f32_fp4 v[42:43], v22, 1.0 op_sel:[0,1,0]
	v_pk_fma_f32 v[44:45], s[4:5], v[46:47], v[44:45] op_sel_hi:[0,1,1]
	v_cvt_scalef32_pk_f32_fp4 v[46:47], v23, 1.0
	v_cvt_scalef32_pk_f32_fp4 v[48:49], v23, 1.0 op_sel:[1,0,0]
	v_cvt_scalef32_pk_f32_fp4 v[50:51], v23, 1.0 op_sel:[0,1,0]
	v_cvt_scalef32_pk_f32_fp4 v[22:23], v23, 1.0 op_sel:[1,1,0]
	v_pk_fma_f32 v[36:37], s[4:5], v[36:37], v[58:59] op_sel_hi:[0,1,1]
	v_pk_fma_f32 v[20:21], s[4:5], v[20:21], v[60:61] op_sel_hi:[0,1,1]
	v_pk_fma_f32 v[38:39], s[4:5], v[38:39], v[62:63] op_sel_hi:[0,1,1]
	v_pk_fma_f32 v[40:41], s[4:5], v[40:41], v[80:81] op_sel_hi:[0,1,1]
	v_pk_fma_f32 v[42:43], s[4:5], v[42:43], v[82:83] op_sel_hi:[0,1,1]
	v_pk_fma_f32 v[46:47], s[4:5], v[46:47], v[56:57] op_sel_hi:[0,1,1]
	v_pk_fma_f32 v[48:49], s[4:5], v[48:49], v[54:55] op_sel_hi:[0,1,1]
	v_pk_fma_f32 v[50:51], s[4:5], v[50:51], v[52:53] op_sel_hi:[0,1,1]
	v_pk_fma_f32 v[22:23], s[4:5], v[22:23], v[84:85] op_sel_hi:[0,1,1]
	v_readlane_b32 s4, v68, 11
	s_waitcnt vmcnt(4)
	v_cvt_scalef32_pk_f32_fp4 v[52:53], v16, 1.0
	v_pk_fma_f32 v[24:25], v[52:53], s[4:5], v[24:25] op_sel_hi:[1,0,1]
	v_cvt_scalef32_pk_f32_fp4 v[52:53], v16, 1.0 op_sel:[1,0,0]
	v_pk_fma_f32 v[26:27], v[52:53], s[4:5], v[26:27] op_sel_hi:[1,0,1]
	v_cvt_scalef32_pk_f32_fp4 v[52:53], v16, 1.0 op_sel:[0,1,0]
	v_pk_fma_f32 v[28:29], s[4:5], v[52:53], v[28:29] op_sel_hi:[0,1,1]
	v_cvt_scalef32_pk_f32_fp4 v[52:53], v16, 1.0 op_sel:[1,1,0]
	v_pk_fma_f32 v[30:31], s[4:5], v[52:53], v[30:31] op_sel_hi:[0,1,1]
	v_cvt_scalef32_pk_f32_fp4 v[52:53], v17, 1.0
	v_pk_fma_f32 v[32:33], s[4:5], v[52:53], v[32:33] op_sel_hi:[0,1,1]
	v_cvt_scalef32_pk_f32_fp4 v[52:53], v17, 1.0 op_sel:[1,0,0]
	v_pk_fma_f32 v[34:35], s[4:5], v[52:53], v[34:35] op_sel_hi:[0,1,1]
	v_cvt_scalef32_pk_f32_fp4 v[52:53], v17, 1.0 op_sel:[0,1,0]
	v_cvt_scalef32_pk_f32_fp4 v[16:17], v17, 1.0 op_sel:[1,1,0]
	v_pk_fma_f32 v[36:37], s[4:5], v[52:53], v[36:37] op_sel_hi:[0,1,1]
	v_pk_fma_f32 v[52:53], s[4:5], v[16:17], v[20:21] op_sel_hi:[0,1,1]
	v_cvt_scalef32_pk_f32_fp4 v[16:17], v18, 1.0
	v_pk_fma_f32 v[38:39], s[4:5], v[16:17], v[38:39] op_sel_hi:[0,1,1]
	v_cvt_scalef32_pk_f32_fp4 v[16:17], v18, 1.0 op_sel:[1,0,0]
	v_pk_fma_f32 v[40:41], s[4:5], v[16:17], v[40:41] op_sel_hi:[0,1,1]
	v_cvt_scalef32_pk_f32_fp4 v[16:17], v18, 1.0 op_sel:[0,1,0]
	v_pk_fma_f32 v[42:43], s[4:5], v[16:17], v[42:43] op_sel_hi:[0,1,1]
	v_cvt_scalef32_pk_f32_fp4 v[16:17], v18, 1.0 op_sel:[1,1,0]
	v_pk_fma_f32 v[44:45], s[4:5], v[16:17], v[44:45] op_sel_hi:[0,1,1]
	v_cvt_scalef32_pk_f32_fp4 v[16:17], v19, 1.0
	v_pk_fma_f32 v[46:47], s[4:5], v[16:17], v[46:47] op_sel_hi:[0,1,1]
	v_cvt_scalef32_pk_f32_fp4 v[16:17], v19, 1.0 op_sel:[1,0,0]
	v_pk_fma_f32 v[48:49], s[4:5], v[16:17], v[48:49] op_sel_hi:[0,1,1]
	v_cvt_scalef32_pk_f32_fp4 v[16:17], v19, 1.0 op_sel:[0,1,0]
	v_pk_fma_f32 v[50:51], s[4:5], v[16:17], v[50:51] op_sel_hi:[0,1,1]
	v_cvt_scalef32_pk_f32_fp4 v[16:17], v19, 1.0 op_sel:[1,1,0]
	s_waitcnt vmcnt(3)
	v_cvt_scalef32_pk_f32_fp4 v[18:19], v12, 1.0 op_sel:[1,0,0]
	v_pk_fma_f32 v[54:55], s[4:5], v[16:17], v[22:23] op_sel_hi:[0,1,1]
	v_readlane_b32 s4, v68, 12
	v_cvt_scalef32_pk_f32_fp4 v[16:17], v12, 1.0
	s_nop 0
	v_pk_fma_f32 v[16:17], v[16:17], s[4:5], v[24:25] op_sel_hi:[1,0,1]
	v_pk_fma_f32 v[18:19], v[18:19], s[4:5], v[26:27] op_sel_hi:[1,0,1]
	v_cvt_scalef32_pk_f32_fp4 v[20:21], v12, 1.0 op_sel:[0,1,0]
	v_cvt_scalef32_pk_f32_fp4 v[22:23], v12, 1.0 op_sel:[1,1,0]
	v_cvt_scalef32_pk_f32_fp4 v[24:25], v13, 1.0
	v_cvt_scalef32_pk_f32_fp4 v[26:27], v13, 1.0 op_sel:[1,0,0]
	v_pk_fma_f32 v[20:21], s[4:5], v[20:21], v[28:29] op_sel_hi:[0,1,1]
	v_pk_fma_f32 v[22:23], s[4:5], v[22:23], v[30:31] op_sel_hi:[0,1,1]
	v_pk_fma_f32 v[24:25], s[4:5], v[24:25], v[32:33] op_sel_hi:[0,1,1]
	v_pk_fma_f32 v[26:27], s[4:5], v[26:27], v[34:35] op_sel_hi:[0,1,1]
	v_cvt_scalef32_pk_f32_fp4 v[28:29], v13, 1.0 op_sel:[0,1,0]
	v_cvt_scalef32_pk_f32_fp4 v[30:31], v14, 1.0
	v_cvt_scalef32_pk_f32_fp4 v[32:33], v14, 1.0 op_sel:[1,0,0]
	v_cvt_scalef32_pk_f32_fp4 v[34:35], v14, 1.0 op_sel:[0,1,0]
	v_pk_fma_f32 v[28:29], s[4:5], v[28:29], v[36:37] op_sel_hi:[0,1,1]
	v_cvt_scalef32_pk_f32_fp4 v[12:13], v13, 1.0 op_sel:[1,1,0]
	v_pk_fma_f32 v[30:31], s[4:5], v[30:31], v[38:39] op_sel_hi:[0,1,1]
	v_pk_fma_f32 v[32:33], s[4:5], v[32:33], v[40:41] op_sel_hi:[0,1,1]
	v_pk_fma_f32 v[34:35], s[4:5], v[34:35], v[42:43] op_sel_hi:[0,1,1]
	v_cvt_scalef32_pk_f32_fp4 v[36:37], v14, 1.0 op_sel:[1,1,0]
	v_cvt_scalef32_pk_f32_fp4 v[38:39], v15, 1.0
	v_cvt_scalef32_pk_f32_fp4 v[40:41], v15, 1.0 op_sel:[1,0,0]
	v_cvt_scalef32_pk_f32_fp4 v[42:43], v15, 1.0 op_sel:[0,1,0]
	v_cvt_scalef32_pk_f32_fp4 v[14:15], v15, 1.0 op_sel:[1,1,0]
	v_pk_fma_f32 v[12:13], s[4:5], v[12:13], v[52:53] op_sel_hi:[0,1,1]
	v_pk_fma_f32 v[36:37], s[4:5], v[36:37], v[44:45] op_sel_hi:[0,1,1]
	v_pk_fma_f32 v[38:39], s[4:5], v[38:39], v[46:47] op_sel_hi:[0,1,1]
	v_pk_fma_f32 v[40:41], s[4:5], v[40:41], v[48:49] op_sel_hi:[0,1,1]
	v_pk_fma_f32 v[42:43], s[4:5], v[42:43], v[50:51] op_sel_hi:[0,1,1]
	v_pk_fma_f32 v[14:15], s[4:5], v[14:15], v[54:55] op_sel_hi:[0,1,1]
	v_readlane_b32 s4, v68, 13
	s_waitcnt vmcnt(2)
	v_cvt_scalef32_pk_f32_fp4 v[44:45], v8, 1.0
	v_pk_fma_f32 v[16:17], v[44:45], s[4:5], v[16:17] op_sel_hi:[1,0,1]
	v_cvt_scalef32_pk_f32_fp4 v[44:45], v8, 1.0 op_sel:[1,0,0]
	v_pk_fma_f32 v[18:19], v[44:45], s[4:5], v[18:19] op_sel_hi:[1,0,1]
	v_cvt_scalef32_pk_f32_fp4 v[44:45], v8, 1.0 op_sel:[0,1,0]
	v_pk_fma_f32 v[20:21], s[4:5], v[44:45], v[20:21] op_sel_hi:[0,1,1]
	v_cvt_scalef32_pk_f32_fp4 v[44:45], v8, 1.0 op_sel:[1,1,0]
	v_pk_fma_f32 v[22:23], s[4:5], v[44:45], v[22:23] op_sel_hi:[0,1,1]
	v_cvt_scalef32_pk_f32_fp4 v[44:45], v9, 1.0
	v_pk_fma_f32 v[24:25], s[4:5], v[44:45], v[24:25] op_sel_hi:[0,1,1]
	v_cvt_scalef32_pk_f32_fp4 v[44:45], v9, 1.0 op_sel:[1,0,0]
	v_pk_fma_f32 v[26:27], s[4:5], v[44:45], v[26:27] op_sel_hi:[0,1,1]
	v_cvt_scalef32_pk_f32_fp4 v[44:45], v9, 1.0 op_sel:[0,1,0]
	v_cvt_scalef32_pk_f32_fp4 v[8:9], v9, 1.0 op_sel:[1,1,0]
	v_pk_fma_f32 v[28:29], s[4:5], v[44:45], v[28:29] op_sel_hi:[0,1,1]
	v_pk_fma_f32 v[44:45], s[4:5], v[8:9], v[12:13] op_sel_hi:[0,1,1]
	v_cvt_scalef32_pk_f32_fp4 v[8:9], v10, 1.0
	v_pk_fma_f32 v[30:31], s[4:5], v[8:9], v[30:31] op_sel_hi:[0,1,1]
	v_cvt_scalef32_pk_f32_fp4 v[8:9], v10, 1.0 op_sel:[1,0,0]
	v_pk_fma_f32 v[32:33], s[4:5], v[8:9], v[32:33] op_sel_hi:[0,1,1]
	v_cvt_scalef32_pk_f32_fp4 v[8:9], v10, 1.0 op_sel:[0,1,0]
	v_pk_fma_f32 v[34:35], s[4:5], v[8:9], v[34:35] op_sel_hi:[0,1,1]
	v_cvt_scalef32_pk_f32_fp4 v[8:9], v10, 1.0 op_sel:[1,1,0]
	v_pk_fma_f32 v[36:37], s[4:5], v[8:9], v[36:37] op_sel_hi:[0,1,1]
	v_cvt_scalef32_pk_f32_fp4 v[8:9], v11, 1.0
	v_pk_fma_f32 v[38:39], s[4:5], v[8:9], v[38:39] op_sel_hi:[0,1,1]
	v_cvt_scalef32_pk_f32_fp4 v[8:9], v11, 1.0 op_sel:[1,0,0]
	v_pk_fma_f32 v[40:41], s[4:5], v[8:9], v[40:41] op_sel_hi:[0,1,1]
	v_cvt_scalef32_pk_f32_fp4 v[8:9], v11, 1.0 op_sel:[0,1,0]
	v_pk_fma_f32 v[42:43], s[4:5], v[8:9], v[42:43] op_sel_hi:[0,1,1]
	v_cvt_scalef32_pk_f32_fp4 v[8:9], v11, 1.0 op_sel:[1,1,0]
	s_waitcnt vmcnt(1)
	v_cvt_scalef32_pk_f32_fp4 v[10:11], v4, 1.0 op_sel:[1,0,0]
	v_pk_fma_f32 v[46:47], s[4:5], v[8:9], v[14:15] op_sel_hi:[0,1,1]
	v_readlane_b32 s4, v68, 14
	v_cvt_scalef32_pk_f32_fp4 v[8:9], v4, 1.0
	s_nop 0
	v_pk_fma_f32 v[8:9], v[8:9], s[4:5], v[16:17] op_sel_hi:[1,0,1]
	v_pk_fma_f32 v[10:11], v[10:11], s[4:5], v[18:19] op_sel_hi:[1,0,1]
	v_cvt_scalef32_pk_f32_fp4 v[12:13], v4, 1.0 op_sel:[0,1,0]
	v_cvt_scalef32_pk_f32_fp4 v[14:15], v4, 1.0 op_sel:[1,1,0]
	v_cvt_scalef32_pk_f32_fp4 v[16:17], v5, 1.0
	v_cvt_scalef32_pk_f32_fp4 v[18:19], v5, 1.0 op_sel:[1,0,0]
	v_pk_fma_f32 v[12:13], s[4:5], v[12:13], v[20:21] op_sel_hi:[0,1,1]
	v_pk_fma_f32 v[14:15], s[4:5], v[14:15], v[22:23] op_sel_hi:[0,1,1]
	v_pk_fma_f32 v[16:17], s[4:5], v[16:17], v[24:25] op_sel_hi:[0,1,1]
	v_pk_fma_f32 v[18:19], s[4:5], v[18:19], v[26:27] op_sel_hi:[0,1,1]
	v_cvt_scalef32_pk_f32_fp4 v[20:21], v5, 1.0 op_sel:[0,1,0]
	v_cvt_scalef32_pk_f32_fp4 v[22:23], v6, 1.0
	v_cvt_scalef32_pk_f32_fp4 v[24:25], v6, 1.0 op_sel:[1,0,0]
	v_cvt_scalef32_pk_f32_fp4 v[26:27], v6, 1.0 op_sel:[0,1,0]
	v_pk_fma_f32 v[20:21], s[4:5], v[20:21], v[28:29] op_sel_hi:[0,1,1]
	v_cvt_scalef32_pk_f32_fp4 v[4:5], v5, 1.0 op_sel:[1,1,0]
	v_pk_fma_f32 v[22:23], s[4:5], v[22:23], v[30:31] op_sel_hi:[0,1,1]
	v_pk_fma_f32 v[24:25], s[4:5], v[24:25], v[32:33] op_sel_hi:[0,1,1]
	v_pk_fma_f32 v[26:27], s[4:5], v[26:27], v[34:35] op_sel_hi:[0,1,1]
	v_cvt_scalef32_pk_f32_fp4 v[28:29], v6, 1.0 op_sel:[1,1,0]
	v_cvt_scalef32_pk_f32_fp4 v[30:31], v7, 1.0
	v_cvt_scalef32_pk_f32_fp4 v[32:33], v7, 1.0 op_sel:[1,0,0]
	v_cvt_scalef32_pk_f32_fp4 v[34:35], v7, 1.0 op_sel:[0,1,0]
	v_cvt_scalef32_pk_f32_fp4 v[6:7], v7, 1.0 op_sel:[1,1,0]
	v_pk_fma_f32 v[4:5], s[4:5], v[4:5], v[44:45] op_sel_hi:[0,1,1]
	v_pk_fma_f32 v[28:29], s[4:5], v[28:29], v[36:37] op_sel_hi:[0,1,1]
	v_pk_fma_f32 v[30:31], s[4:5], v[30:31], v[38:39] op_sel_hi:[0,1,1]
	v_pk_fma_f32 v[32:33], s[4:5], v[32:33], v[40:41] op_sel_hi:[0,1,1]
	v_pk_fma_f32 v[34:35], s[4:5], v[34:35], v[42:43] op_sel_hi:[0,1,1]
	v_pk_fma_f32 v[6:7], s[4:5], v[6:7], v[46:47] op_sel_hi:[0,1,1]
	v_readlane_b32 s4, v68, 15
	s_waitcnt vmcnt(0)
	v_cvt_scalef32_pk_f32_fp4 v[36:37], v0, 1.0
	v_pk_fma_f32 v[110:111], v[36:37], s[4:5], v[8:9] op_sel_hi:[1,0,1]
	v_cvt_scalef32_pk_f32_fp4 v[8:9], v0, 1.0 op_sel:[1,0,0]
	v_pk_fma_f32 v[108:109], v[8:9], s[4:5], v[10:11] op_sel_hi:[1,0,1]
	v_cvt_scalef32_pk_f32_fp4 v[8:9], v0, 1.0 op_sel:[0,1,0]
	v_pk_fma_f32 v[106:107], s[4:5], v[8:9], v[12:13] op_sel_hi:[0,1,1]
	v_cvt_scalef32_pk_f32_fp4 v[8:9], v0, 1.0 op_sel:[1,1,0]
	v_pk_fma_f32 v[104:105], s[4:5], v[8:9], v[14:15] op_sel_hi:[0,1,1]
	v_cvt_scalef32_pk_f32_fp4 v[8:9], v1, 1.0
	v_pk_fma_f32 v[102:103], s[4:5], v[8:9], v[16:17] op_sel_hi:[0,1,1]
	v_cvt_scalef32_pk_f32_fp4 v[8:9], v1, 1.0 op_sel:[1,0,0]
	s_nop 0
	v_pk_fma_f32 v[100:101], s[4:5], v[8:9], v[18:19] op_sel_hi:[0,1,1]
	v_cvt_scalef32_pk_f32_fp4 v[8:9], v1, 1.0 op_sel:[0,1,0]
	v_cvt_scalef32_pk_f32_fp4 v[0:1], v1, 1.0 op_sel:[1,1,0]
	v_pk_fma_f32 v[96:97], s[4:5], v[0:1], v[4:5] op_sel_hi:[0,1,1]
	v_cvt_scalef32_pk_f32_fp4 v[0:1], v2, 1.0
	v_pk_fma_f32 v[94:95], s[4:5], v[0:1], v[22:23] op_sel_hi:[0,1,1]
	v_cvt_scalef32_pk_f32_fp4 v[0:1], v2, 1.0 op_sel:[1,0,0]
	v_pk_fma_f32 v[92:93], s[4:5], v[0:1], v[24:25] op_sel_hi:[0,1,1]
	v_cvt_scalef32_pk_f32_fp4 v[0:1], v2, 1.0 op_sel:[0,1,0]
	v_pk_fma_f32 v[90:91], s[4:5], v[0:1], v[26:27] op_sel_hi:[0,1,1]
	v_cvt_scalef32_pk_f32_fp4 v[0:1], v2, 1.0 op_sel:[1,1,0]
	v_pk_fma_f32 v[98:99], s[4:5], v[8:9], v[20:21] op_sel_hi:[0,1,1]
	v_pk_fma_f32 v[88:89], s[4:5], v[0:1], v[28:29] op_sel_hi:[0,1,1]
	v_cvt_scalef32_pk_f32_fp4 v[0:1], v3, 1.0
	v_pk_fma_f32 v[86:87], s[4:5], v[0:1], v[30:31] op_sel_hi:[0,1,1]
	v_cvt_scalef32_pk_f32_fp4 v[0:1], v3, 1.0 op_sel:[1,0,0]
	v_pk_fma_f32 v[84:85], s[4:5], v[0:1], v[32:33] op_sel_hi:[0,1,1]
	v_cvt_scalef32_pk_f32_fp4 v[0:1], v3, 1.0 op_sel:[0,1,0]
	v_pk_fma_f32 v[82:83], s[4:5], v[0:1], v[34:35] op_sel_hi:[0,1,1]
	v_cvt_scalef32_pk_f32_fp4 v[0:1], v3, 1.0 op_sel:[1,1,0]
	v_pk_fma_f32 v[80:81], s[4:5], v[0:1], v[6:7] op_sel_hi:[0,1,1]
	s_cbranch_scc1 .LBB0_986
; __device__ __forceinline__ f32x4 unpk4(uint2 u) { f32x4 r; r[0] = __uint_as_float(u.x << 16); r[1] = __uint_as_float(u.x & 0xffff0000u); r[2] = __uint_as_float(u.y << 16); r[3] = __uint_as_float(u.y & 0xffff0000u); return r; }
; __device__ __forceinline__ uint4 pk8(f32x4 a, f32x4 b) { return make_uint4(cvt_pk_bf16(a[0], a[1]), cvt_pk_bf16(a[2], a[3]), cvt_pk_bf16(b[0], b[1]), cvt_pk_bf16(b[2], b[3])); }
; __device__ void phase_peer(const Params& P, unsigned char* smem) {
;     ...
;             float ss2 = 0.f;
; #pragma unroll
;             for (int q = 0; q < 4; ++q) {
;                 const uint4 h8 = *(const uint4*)(hrow + q * 8);
;                 f32x4 a = unpk4(make_uint2(h8.x, h8.y)), b = unpk4(make_uint2(h8.z, h8.w));
;                 a[0] += y2[q * 4][0]; a[1] += y2[q * 4][1]; a[2] += y2[q * 4 + 1][0]; a[3] += y2[q * 4 + 1][1];
;                 b[0] += y2[q * 4 + 2][0]; b[1] += y2[q * 4 + 2][1]; b[2] += y2[q * 4 + 3][0]; b[3] += y2[q * 4 + 3][1];
;                 ss2 += a[0] * a[0] + a[1] * a[1] + a[2] * a[2] + a[3] * a[3] + b[0] * b[0] + b[1] * b[1] + b[2] * b[2] + b[3] * b[3];
;                 *(uint4*)(hrow + q * 8) = pk8(a, b);
;             }
;             ss2 = wave_sum(ss2);
;             if (lane == 0) rinv3[gtok] = rsqrtf(ss2 * (1.f / D) + EPS);
	v_lshl_add_u32 v68, s16, 3, v146
	v_lshl_add_u64 v[0:1], v[68:69], 0, s[10:11]
	v_lshlrev_b64 v[2:3], 12, v[0:1]
	v_lshl_add_u64 v[2:3], v[64:65], 0, v[2:3]
	global_load_dwordx4 v[4:7], v[2:3], off
	v_and_b32_e32 v36, 64, v112
	v_xor_b32_e32 v37, 32, v112
	v_add_u32_e32 v36, 64, v36
	v_cmp_lt_i32_e64 s[0:1], v37, v36
	v_xor_b32_e32 v38, 16, v112
	s_waitcnt vmcnt(0)
	v_lshlrev_b32_e32 v8, 16, v4
	v_and_b32_e32 v4, 0xffff0000, v4
	v_lshlrev_b32_e32 v9, 16, v5
	v_and_b32_e32 v5, 0xffff0000, v5
	v_lshlrev_b32_e32 v10, 16, v6
	v_and_b32_e32 v6, 0xffff0000, v6
	v_lshlrev_b32_e32 v11, 16, v7
	v_and_b32_e32 v7, 0xffff0000, v7
	v_add_f32_e32 v12, v110, v8
	v_add_f32_e32 v13, v111, v4
	v_add_f32_e32 v14, v108, v9
	v_add_f32_e32 v15, v109, v5
	v_add_f32_e32 v16, v106, v10
	v_add_f32_e32 v17, v107, v6
	v_add_f32_e32 v18, v104, v11
	v_add_f32_e32 v19, v105, v7
	v_cvt_pk_bf16_f32 v4, v12, v13
	v_cvt_pk_bf16_f32 v5, v14, v15
	v_cvt_pk_bf16_f32 v6, v16, v17
	v_cvt_pk_bf16_f32 v7, v18, v19
	global_load_dwordx4 v[8:11], v[2:3], off offset:1024
	v_mul_f32_e32 v13, v13, v13
	global_store_dwordx4 v[2:3], v[4:7], off
	v_fmac_f32_e32 v13, v12, v12
	v_fmac_f32_e32 v13, v14, v14
	v_fmac_f32_e32 v13, v15, v15
	v_fmac_f32_e32 v13, v16, v16
	v_fmac_f32_e32 v13, v17, v17
	v_fmac_f32_e32 v13, v18, v18
	v_fmac_f32_e32 v13, v19, v19
	v_cndmask_b32_e64 v37, v112, v37, s[0:1]
	v_lshlrev_b32_e32 v37, 2, v37
	v_cmp_lt_i32_e64 s[0:1], v38, v36
	v_xor_b32_e32 v18, 8, v112
	s_waitcnt vmcnt(1)
	v_lshlrev_b32_e32 v4, 16, v8
	v_and_b32_e32 v5, 0xffff0000, v8
	v_lshlrev_b32_e32 v6, 16, v9
	v_and_b32_e32 v7, 0xffff0000, v9
	v_lshlrev_b32_e32 v8, 16, v10
	v_and_b32_e32 v9, 0xffff0000, v10
	v_lshlrev_b32_e32 v10, 16, v11
	v_and_b32_e32 v11, 0xffff0000, v11
	v_add_f32_e32 v20, v102, v4
	v_add_f32_e32 v21, v103, v5
	v_add_f32_e32 v22, v100, v6
	v_add_f32_e32 v23, v101, v7
	v_add_f32_e32 v24, v98, v8
	v_add_f32_e32 v25, v99, v9
	v_add_f32_e32 v26, v96, v10
	v_add_f32_e32 v27, v97, v11
	v_cvt_pk_bf16_f32 v4, v20, v21
	v_cvt_pk_bf16_f32 v5, v22, v23
	v_cvt_pk_bf16_f32 v6, v24, v25
	v_cvt_pk_bf16_f32 v7, v26, v27
	global_load_dwordx4 v[8:11], v[2:3], off offset:2048
	v_mul_f32_e32 v12, v21, v21
	global_store_dwordx4 v[2:3], v[4:7], off offset:1024
	v_fmac_f32_e32 v12, v20, v20
	v_fmac_f32_e32 v12, v22, v22
	v_fmac_f32_e32 v12, v23, v23
	v_fmac_f32_e32 v12, v24, v24
	v_fmac_f32_e32 v12, v25, v25
	v_fmac_f32_e32 v12, v26, v26
	v_fmac_f32_e32 v12, v27, v27
	v_add_f32_e32 v12, v13, v12
	v_cndmask_b32_e64 v19, v112, v38, s[0:1]
	v_lshlrev_b32_e32 v19, 2, v19
	v_cmp_lt_i32_e64 s[0:1], v18, v36
	s_waitcnt vmcnt(1)
	v_lshlrev_b32_e32 v4, 16, v8
	v_and_b32_e32 v5, 0xffff0000, v8
	v_lshlrev_b32_e32 v6, 16, v9
	v_and_b32_e32 v7, 0xffff0000, v9
	v_lshlrev_b32_e32 v8, 16, v10
	v_and_b32_e32 v9, 0xffff0000, v10
	v_lshlrev_b32_e32 v10, 16, v11
	v_and_b32_e32 v11, 0xffff0000, v11
	v_add_f32_e32 v28, v94, v4
	v_add_f32_e32 v29, v95, v5
	v_add_f32_e32 v30, v92, v6
	v_add_f32_e32 v31, v93, v7
	v_add_f32_e32 v32, v90, v8
	v_add_f32_e32 v33, v91, v9
	v_add_f32_e32 v34, v88, v10
	v_add_f32_e32 v35, v89, v11
	v_cvt_pk_bf16_f32 v4, v28, v29
	v_cvt_pk_bf16_f32 v5, v30, v31
	v_cvt_pk_bf16_f32 v6, v32, v33
	v_cvt_pk_bf16_f32 v7, v34, v35
	global_load_dwordx4 v[8:11], v[2:3], off offset:3072
	v_mul_f32_e32 v13, v29, v29
	v_fmac_f32_e32 v13, v28, v28
	v_fmac_f32_e32 v13, v30, v30
	v_fmac_f32_e32 v13, v31, v31
	v_fmac_f32_e32 v13, v32, v32
	v_fmac_f32_e32 v13, v33, v33
	v_fmac_f32_e32 v13, v34, v34
	v_fmac_f32_e32 v13, v35, v35
	v_add_f32_e32 v12, v12, v13
	v_cndmask_b32_e64 v18, v112, v18, s[0:1]
	v_lshlrev_b32_e32 v18, 2, v18
	global_store_dwordx4 v[2:3], v[4:7], off offset:2048
	s_waitcnt vmcnt(1)
	v_lshlrev_b32_e32 v13, 16, v8
	v_and_b32_e32 v8, 0xffff0000, v8
	v_add_f32_e32 v8, v87, v8
	v_lshlrev_b32_e32 v14, 16, v9
	v_add_f32_e32 v13, v86, v13
	v_mul_f32_e32 v17, v8, v8
	v_and_b32_e32 v9, 0xffff0000, v9
	v_add_f32_e32 v14, v84, v14
	v_fmac_f32_e32 v17, v13, v13
	v_lshlrev_b32_e32 v15, 16, v10
	v_add_f32_e32 v9, v85, v9
	v_fmac_f32_e32 v17, v14, v14
	v_and_b32_e32 v10, 0xffff0000, v10
	v_add_f32_e32 v15, v82, v15
	v_fmac_f32_e32 v17, v9, v9
	v_lshlrev_b32_e32 v16, 16, v11
	v_add_f32_e32 v10, v83, v10
	v_fmac_f32_e32 v17, v15, v15
	v_and_b32_e32 v11, 0xffff0000, v11
	v_add_f32_e32 v16, v80, v16
	v_fmac_f32_e32 v17, v10, v10
	v_add_f32_e32 v11, v81, v11
	v_fmac_f32_e32 v17, v16, v16
	v_fmac_f32_e32 v17, v11, v11
	v_add_f32_e32 v12, v12, v17
	ds_bpermute_b32 v17, v37, v12
	v_cvt_pk_bf16_f32 v6, v13, v8
	v_cvt_pk_bf16_f32 v7, v14, v9
	v_cvt_pk_bf16_f32 v8, v15, v10
	v_cvt_pk_bf16_f32 v9, v16, v11
	s_waitcnt lgkmcnt(0)
	v_add_f32_e32 v12, v12, v17
	ds_bpermute_b32 v17, v19, v12
	v_xor_b32_e32 v19, 4, v112
	v_cmp_lt_i32_e64 s[0:1], v19, v36
	global_store_dwordx4 v[2:3], v[6:9], off offset:3072
	s_waitcnt lgkmcnt(0)
	v_add_f32_e32 v12, v12, v17
	ds_bpermute_b32 v17, v18, v12
	v_cndmask_b32_e64 v19, v112, v19, s[0:1]
	v_lshlrev_b32_e32 v19, 2, v19
	v_xor_b32_e32 v18, 2, v112
	v_cmp_lt_i32_e64 s[0:1], v18, v36
	s_waitcnt lgkmcnt(0)
	v_add_f32_e32 v12, v12, v17
	ds_bpermute_b32 v17, v19, v12
	v_cndmask_b32_e64 v18, v112, v18, s[0:1]
	v_lshlrev_b32_e32 v18, 2, v18
	v_xor_b32_e32 v19, 1, v112
	v_cmp_lt_i32_e64 s[0:1], v19, v36
	s_waitcnt lgkmcnt(0)
	v_add_f32_e32 v12, v12, v17
	ds_bpermute_b32 v17, v18, v12
	v_cndmask_b32_e64 v18, v112, v19, s[0:1]
	v_lshlrev_b32_e32 v5, 2, v18
	s_waitcnt lgkmcnt(0)
	v_add_f32_e32 v4, v12, v17
	ds_bpermute_b32 v5, v5, v4
	s_and_saveexec_b64 s[12:13], vcc
	s_cbranch_execz .LBB0_984
	s_waitcnt lgkmcnt(0)
	v_add_f32_e32 v2, v4, v5
	v_fmamk_f32 v2, v2, 0x3a000000, v113
	v_mul_f32_e32 v3, 0x4b800000, v2
	v_cmp_gt_f32_e64 s[0:1], s14, v2
	v_lshl_add_u64 v[0:1], v[0:1], 2, s[26:27]
	s_nop 0
	v_cndmask_b32_e64 v2, v2, v3, s[0:1]
	v_rsq_f32_e32 v2, v2
	s_nop 0
	v_mul_f32_e32 v3, 0x45800000, v2
	v_cndmask_b32_e64 v2, v2, v3, s[0:1]
	global_store_dword v[0:1], v2, off
	s_branch .LBB0_984
